# EpiVt epilogue with packed f32 math (v_pk_mul/fma/add), interleaving DPP final step; dtype comment at top
# baseline (speedup 1.0000x reference)
; #define PG8_STAGE(bufoff, gbase, voff) do { _Pragma("unroll") for (int _i = 0; _i < 2; ++_i) \
;         __builtin_amdgcn_global_load_lds((const __attribute__((address_space(1))) unsigned*)((const char*)(gbase) + (voff)[_i]), (LAS unsigned*)(lds + (bufoff) + ldsw + _i * 8192), 16, 0, 0); } while (0)
; #define PG8_LDA(dst, b, h) do { _Pragma("unroll") for (int m = 0; m < 4; ++m) _Pragma("unroll") for (int k = 0; k < 2; ++k) dst[m][k] = *(const LAS bf16x8*)(lds + PG8_SA(b, h) + aoff + m * 2048 + k * 1024); } while (0)
; #define PG8_LDB(dst, b, h) do { _Pragma("unroll") for (int n = 0; n < 2; ++n) _Pragma("unroll") for (int k = 0; k < 2; ++k) dst[n][k] = *(const LAS bf16x8*)(lds + PG8_SB(b, h) + boff + n * 2048 + k * 1024); } while (0)
; #define PG8_MMA(ai, bj, At, Bt) do { __builtin_amdgcn_s_setprio(1); _Pragma("unroll") for (int m = 0; m < 4; ++m) _Pragma("unroll") for (int n = 0; n < 2; ++n) _Pragma("unroll") for (int k = 0; k < 2; ++k) \
;         acc[ai][bj][m][n] = __builtin_amdgcn_mfma_f32_16x16x32_bf16(Bt[n][k], At[m][k], acc[ai][bj][m][n], 0, 0, 0); __builtin_amdgcn_s_setprio(0); } while (0)
; #define PG8_WAIT_V(n) asm volatile("s_waitcnt vmcnt(" #n ")" ::: "memory")
; #define PG8_WAIT_L(n) asm volatile("s_waitcnt lgkmcnt(" #n ")" ::: "memory")
; #define PG8_BAR __builtin_amdgcn_s_barrier()
; #define PG8_SCHED __builtin_amdgcn_sched_barrier(0)
; template <class Epi>
; __device__ __forceinline__ void gemm_phase(LAS unsigned char* lds, const Gemm g, const StaticOrder& S_in, const Epi& E, int sw) {
;     ...
;             PG8_LDB(B0, 0, 0); PG8_SCHED; PG8_LDA(At, 0, 0); PG8_STAGE(PG8_SA(1, 1), a1 + hstepA, voffA);
;             PG8_WAIT_L(8); PG8_BAR; PG8_WAIT_L(0); PG8_MMA(0, 0, At, B0); PG8_BAR; PG8_SCHED;
;             PG8_LDB(B1, 0, 1); PG8_STAGE(PG8_SB(0, 0), b2, voffB);
;             PG8_BAR; PG8_WAIT_L(0); PG8_MMA(0, 1, At, B1); PG8_BAR;
;             PG8_LDA(At, 0, 1); PG8_STAGE(PG8_SA(0, 0), a2, voffA);
;             PG8_BAR; PG8_WAIT_L(0); PG8_MMA(1, 0, At, B0); PG8_BAR; PG8_SCHED;
;             PG8_STAGE(PG8_SB(0, 1), b2 + hstepB, voffB);
;             PG8_WAIT_V(6); PG8_BAR; PG8_MMA(1, 1, At, B1); PG8_BAR;
.LBB0_771:
	s_add_u32 s20, s0, 0xfffc0080
	s_addc_u32 s21, s1, -1
	s_add_i32 s51, 0, 0x10000
	v_add_u32_e32 v0, s51, v171
	ds_read_b128 v[142:145], v0
	ds_read_b128 v[146:149], v0 offset:1024
	ds_read_b128 v[150:153], v0 offset:2048
	ds_read_b128 v[154:157], v0 offset:3072
	s_cmp_eq_u32 s50, 12
	s_cselect_b32 s23, s9, s21
	s_cselect_b32 s22, s17, s20
	s_cselect_b32 s21, s7, s49
	s_cselect_b32 s20, s19, s48
	v_lshl_add_u64 v[192:193], s[0:1], 0, v[138:139]
	s_add_i32 m0, s34, 0xc000
	ds_read_b128 v[158:161], v232
	ds_read_b128 v[162:165], v232 offset:1024
	ds_read_b128 v[166:169], v232 offset:2048
	ds_read_b128 v[172:175], v232 offset:3072
	ds_read_b128 v[176:179], v232 offset:4096
	ds_read_b128 v[180:183], v232 offset:5120
	ds_read_b128 v[184:187], v232 offset:6144
	ds_read_b128 v[188:191], v232 offset:7168
	global_load_lds_dwordx4 v[192:193], off
	v_lshl_add_u64 v[192:193], s[0:1], 0, v[140:141]
	s_add_i32 m0, s34, 0xe000
	s_nop 0
	global_load_lds_dwordx4 v[192:193], off
	s_waitcnt lgkmcnt(8)
	s_barrier
	s_waitcnt lgkmcnt(0)
	s_setprio 1
	s_waitcnt lgkmcnt(0)
	v_mfma_f32_16x16x32_bf16 v[126:129], v[142:145], v[158:161], v[126:129]
	v_mfma_f32_16x16x32_bf16 v[122:125], v[150:153], v[158:161], v[122:125]
	v_mfma_f32_16x16x32_bf16 v[118:121], v[142:145], v[166:169], v[118:121]
	v_mfma_f32_16x16x32_bf16 v[114:117], v[150:153], v[166:169], v[114:117]
	v_mfma_f32_16x16x32_bf16 v[90:93], v[142:145], v[176:179], v[90:93]
	v_mfma_f32_16x16x32_bf16 v[110:113], v[150:153], v[176:179], v[110:113]
	v_mfma_f32_16x16x32_bf16 v[86:89], v[142:145], v[184:187], v[86:89]
	v_mfma_f32_16x16x32_bf16 v[106:109], v[150:153], v[184:187], v[106:109]
	v_mfma_f32_16x16x32_bf16 v[126:129], v[146:149], v[162:165], v[126:129]
	v_mfma_f32_16x16x32_bf16 v[122:125], v[154:157], v[162:165], v[122:125]
	v_mfma_f32_16x16x32_bf16 v[118:121], v[146:149], v[172:175], v[118:121]
	v_mfma_f32_16x16x32_bf16 v[114:117], v[154:157], v[172:175], v[114:117]
	v_mfma_f32_16x16x32_bf16 v[90:93], v[146:149], v[180:183], v[90:93]
	v_mfma_f32_16x16x32_bf16 v[110:113], v[154:157], v[180:183], v[110:113]
	v_mfma_f32_16x16x32_bf16 v[86:89], v[146:149], v[188:191], v[86:89]
	v_mfma_f32_16x16x32_bf16 v[106:109], v[154:157], v[188:191], v[106:109]
	s_setprio 0
	s_barrier
	s_add_i32 s54, 0, 0x14000
	s_add_i32 s51, s51, s29
	v_add_u32_e32 v0, s54, v171
	v_lshl_add_u64 v[208:209], s[20:21], 0, v[132:133]
	s_mov_b32 m0, s51
	ds_read_b128 v[192:195], v0
	ds_read_b128 v[196:199], v0 offset:1024
	ds_read_b128 v[200:203], v0 offset:2048
	ds_read_b128 v[204:207], v0 offset:3072
	global_load_lds_dwordx4 v[208:209], off
	v_lshl_add_u64 v[210:211], s[20:21], 0, v[136:137]
	s_add_i32 m0, s51, 0x2000
	s_nop 0
	global_load_lds_dwordx4 v[210:211], off
	s_barrier
	s_waitcnt lgkmcnt(0)
	s_setprio 1
	s_waitcnt lgkmcnt(0)
	v_mfma_f32_16x16x32_bf16 v[62:65], v[192:195], v[158:161], v[62:65]
	v_mfma_f32_16x16x32_bf16 v[58:61], v[200:203], v[158:161], v[58:61]
	v_mfma_f32_16x16x32_bf16 v[54:57], v[192:195], v[166:169], v[54:57]
	v_mfma_f32_16x16x32_bf16 v[50:53], v[200:203], v[166:169], v[50:53]
	v_mfma_f32_16x16x32_bf16 v[26:29], v[192:195], v[176:179], v[26:29]
	v_mfma_f32_16x16x32_bf16 v[46:49], v[200:203], v[176:179], v[46:49]
	v_mfma_f32_16x16x32_bf16 v[22:25], v[192:195], v[184:187], v[22:25]
	v_mfma_f32_16x16x32_bf16 v[42:45], v[200:203], v[184:187], v[42:45]
	v_mfma_f32_16x16x32_bf16 v[62:65], v[196:199], v[162:165], v[62:65]
	v_mfma_f32_16x16x32_bf16 v[58:61], v[204:207], v[162:165], v[58:61]
	v_mfma_f32_16x16x32_bf16 v[54:57], v[196:199], v[172:175], v[54:57]
	v_mfma_f32_16x16x32_bf16 v[50:53], v[204:207], v[172:175], v[50:53]
	v_mfma_f32_16x16x32_bf16 v[26:29], v[196:199], v[180:183], v[26:29]
	v_mfma_f32_16x16x32_bf16 v[46:49], v[204:207], v[180:183], v[46:49]
	v_mfma_f32_16x16x32_bf16 v[22:25], v[196:199], v[188:191], v[22:25]
	v_mfma_f32_16x16x32_bf16 v[42:45], v[204:207], v[188:191], v[42:45]
	s_setprio 0
	s_mov_b32 m0, s34
	v_lshl_add_u64 v[212:213], s[22:23], 0, v[130:131]
	s_barrier
	ds_read_b128 v[158:161], v232 offset:16384
	ds_read_b128 v[162:165], v232 offset:17408
	ds_read_b128 v[166:169], v232 offset:18432
	ds_read_b128 v[172:175], v232 offset:19456
	ds_read_b128 v[176:179], v232 offset:20480
	ds_read_b128 v[180:183], v232 offset:21504
	ds_read_b128 v[184:187], v232 offset:22528
	ds_read_b128 v[188:191], v232 offset:23552
	global_load_lds_dwordx4 v[212:213], off
	v_lshl_add_u64 v[214:215], s[22:23], 0, v[134:135]
	s_mov_b32 m0, s35
	s_nop 0
	global_load_lds_dwordx4 v[214:215], off
	s_barrier
	s_waitcnt lgkmcnt(0)
	s_setprio 1
	s_waitcnt lgkmcnt(0)
	v_mfma_f32_16x16x32_bf16 v[78:81], v[142:145], v[158:161], v[78:81]
	v_mfma_f32_16x16x32_bf16 v[102:105], v[150:153], v[158:161], v[102:105]
	v_mfma_f32_16x16x32_bf16 v[74:77], v[142:145], v[166:169], v[74:77]
	v_mfma_f32_16x16x32_bf16 v[98:101], v[150:153], v[166:169], v[98:101]
	v_mfma_f32_16x16x32_bf16 v[70:73], v[142:145], v[176:179], v[70:73]
	v_mfma_f32_16x16x32_bf16 v[94:97], v[150:153], v[176:179], v[94:97]
	v_mfma_f32_16x16x32_bf16 v[66:69], v[142:145], v[184:187], v[66:69]
	v_mfma_f32_16x16x32_bf16 v[82:85], v[150:153], v[184:187], v[82:85]
	v_mfma_f32_16x16x32_bf16 v[78:81], v[146:149], v[162:165], v[78:81]
	v_mfma_f32_16x16x32_bf16 v[102:105], v[154:157], v[162:165], v[102:105]
	v_mfma_f32_16x16x32_bf16 v[74:77], v[146:149], v[172:175], v[74:77]
	v_mfma_f32_16x16x32_bf16 v[98:101], v[154:157], v[172:175], v[98:101]
	v_mfma_f32_16x16x32_bf16 v[70:73], v[146:149], v[180:183], v[70:73]
	v_mfma_f32_16x16x32_bf16 v[94:97], v[154:157], v[180:183], v[94:97]
	v_mfma_f32_16x16x32_bf16 v[66:69], v[146:149], v[188:191], v[66:69]
	v_mfma_f32_16x16x32_bf16 v[82:85], v[154:157], v[188:191], v[82:85]
	s_setprio 0
	s_barrier
; #define PG8_STAGE(bufoff, gbase, voff) do { _Pragma("unroll") for (int _i = 0; _i < 2; ++_i) \
;         __builtin_amdgcn_global_load_lds((const __attribute__((address_space(1))) unsigned*)((const char*)(gbase) + (voff)[_i]), (LAS unsigned*)(lds + (bufoff) + ldsw + _i * 8192), 16, 0, 0); } while (0)
; #define PG8_LDA(dst, b, h) do { _Pragma("unroll") for (int m = 0; m < 4; ++m) _Pragma("unroll") for (int k = 0; k < 2; ++k) dst[m][k] = *(const LAS bf16x8*)(lds + PG8_SA(b, h) + aoff + m * 2048 + k * 1024); } while (0)
; #define PG8_LDB(dst, b, h) do { _Pragma("unroll") for (int n = 0; n < 2; ++n) _Pragma("unroll") for (int k = 0; k < 2; ++k) dst[n][k] = *(const LAS bf16x8*)(lds + PG8_SB(b, h) + boff + n * 2048 + k * 1024); } while (0)
; #define PG8_MMA(ai, bj, At, Bt) do { __builtin_amdgcn_s_setprio(1); _Pragma("unroll") for (int m = 0; m < 4; ++m) _Pragma("unroll") for (int n = 0; n < 2; ++n) _Pragma("unroll") for (int k = 0; k < 2; ++k) \
;         acc[ai][bj][m][n] = __builtin_amdgcn_mfma_f32_16x16x32_bf16(Bt[n][k], At[m][k], acc[ai][bj][m][n], 0, 0, 0); __builtin_amdgcn_s_setprio(0); } while (0)
; #define PG8_WAIT_V(n) asm volatile("s_waitcnt vmcnt(" #n ")" ::: "memory")
; #define PG8_WAIT_L(n) asm volatile("s_waitcnt lgkmcnt(" #n ")" ::: "memory")
; #define PG8_BAR __builtin_amdgcn_s_barrier()
; #define PG8_SCHED __builtin_amdgcn_sched_barrier(0)
; template <class Epi>
; __device__ __forceinline__ void gemm_phase(LAS unsigned char* lds, const Gemm g, const StaticOrder& S_in, const Epi& E, int sw) {
;     ...
;             PG8_STAGE(PG8_SB(0, 1), b2 + hstepB, voffB);
;             PG8_WAIT_V(6); PG8_BAR; PG8_MMA(1, 1, At, B1); PG8_BAR;
;             PG8_LDB(B0, 1, 0); PG8_SCHED; PG8_LDA(At, 1, 0); PG8_STAGE(PG8_SA(0, 1), a2 + hstepA, voffA);
;             PG8_WAIT_L(8); PG8_BAR; PG8_WAIT_L(0); PG8_MMA(0, 0, At, B0); PG8_BAR; PG8_SCHED;
;             PG8_LDB(B1, 1, 1); PG8_STAGE(PG8_SB(1, 0), b3, voffB);
;             PG8_BAR; PG8_WAIT_L(0); PG8_MMA(0, 1, At, B1); PG8_BAR;
;             PG8_LDA(At, 1, 1); PG8_STAGE(PG8_SA(1, 0), a3, voffA);
;             PG8_BAR; PG8_WAIT_L(0); PG8_MMA(1, 0, At, B0); PG8_BAR; PG8_SCHED;
	s_add_u32 s52, s20, 0x40000
	s_addc_u32 s53, s21, 0
	s_add_i32 s51, s54, s29
	v_lshl_add_u64 v[142:143], s[52:53], 0, v[132:133]
	s_mov_b32 m0, s51
	s_nop 0
	global_load_lds_dwordx4 v[142:143], off
	v_lshl_add_u64 v[142:143], s[52:53], 0, v[136:137]
	s_add_i32 m0, s51, 0x2000
	s_nop 0
	global_load_lds_dwordx4 v[142:143], off
	s_waitcnt vmcnt(6)
	s_barrier
	s_setprio 1
	v_mfma_f32_16x16x32_bf16 v[14:17], v[192:195], v[158:161], v[14:17]
	v_mfma_f32_16x16x32_bf16 v[38:41], v[200:203], v[158:161], v[38:41]
	v_mfma_f32_16x16x32_bf16 v[10:13], v[192:195], v[166:169], v[10:13]
	v_mfma_f32_16x16x32_bf16 v[34:37], v[200:203], v[166:169], v[34:37]
	v_mfma_f32_16x16x32_bf16 v[6:9], v[192:195], v[176:179], v[6:9]
	v_mfma_f32_16x16x32_bf16 v[30:33], v[200:203], v[176:179], v[30:33]
	v_mfma_f32_16x16x32_bf16 v[2:5], v[192:195], v[184:187], v[2:5]
	v_mfma_f32_16x16x32_bf16 v[18:21], v[200:203], v[184:187], v[18:21]
	v_mfma_f32_16x16x32_bf16 v[14:17], v[196:199], v[162:165], v[14:17]
	v_mfma_f32_16x16x32_bf16 v[38:41], v[204:207], v[162:165], v[38:41]
	v_mfma_f32_16x16x32_bf16 v[10:13], v[196:199], v[172:175], v[10:13]
	v_mfma_f32_16x16x32_bf16 v[34:37], v[204:207], v[172:175], v[34:37]
	v_mfma_f32_16x16x32_bf16 v[6:9], v[196:199], v[180:183], v[6:9]
	v_mfma_f32_16x16x32_bf16 v[30:33], v[204:207], v[180:183], v[30:33]
	v_mfma_f32_16x16x32_bf16 v[2:5], v[196:199], v[188:191], v[2:5]
	v_mfma_f32_16x16x32_bf16 v[18:21], v[204:207], v[188:191], v[18:21]
	s_setprio 0
	s_add_i32 s51, 0, 0x18000
	v_add_u32_e32 v0, s51, v171
	s_barrier
	ds_read_b128 v[142:145], v0
	ds_read_b128 v[146:149], v0 offset:1024
	ds_read_b128 v[150:153], v0 offset:2048
	ds_read_b128 v[154:157], v0 offset:3072
	s_add_u32 s22, s22, 0x40000
	s_addc_u32 s23, s23, 0
	s_mov_b32 m0, s36
	v_lshl_add_u64 v[192:193], s[22:23], 0, v[130:131]
	ds_read_b128 v[158:161], v232 offset:32768
	ds_read_b128 v[162:165], v232 offset:33792
	ds_read_b128 v[166:169], v232 offset:34816
	ds_read_b128 v[172:175], v232 offset:35840
	ds_read_b128 v[176:179], v232 offset:36864
	ds_read_b128 v[180:183], v232 offset:37888
	ds_read_b128 v[184:187], v232 offset:38912
	ds_read_b128 v[188:191], v232 offset:39936
	global_load_lds_dwordx4 v[192:193], off
	v_lshl_add_u64 v[192:193], s[22:23], 0, v[134:135]
	s_mov_b32 m0, s37
	s_nop 0
	global_load_lds_dwordx4 v[192:193], off
	s_waitcnt lgkmcnt(8)
	s_barrier
	s_waitcnt lgkmcnt(0)
	s_setprio 1
	s_waitcnt lgkmcnt(0)
	v_mfma_f32_16x16x32_bf16 v[126:129], v[142:145], v[158:161], v[126:129]
	v_mfma_f32_16x16x32_bf16 v[122:125], v[150:153], v[158:161], v[122:125]
	v_mfma_f32_16x16x32_bf16 v[118:121], v[142:145], v[166:169], v[118:121]
	v_mfma_f32_16x16x32_bf16 v[114:117], v[150:153], v[166:169], v[114:117]
	v_mfma_f32_16x16x32_bf16 v[90:93], v[142:145], v[176:179], v[90:93]
	v_mfma_f32_16x16x32_bf16 v[110:113], v[150:153], v[176:179], v[110:113]
	v_mfma_f32_16x16x32_bf16 v[86:89], v[142:145], v[184:187], v[86:89]
	v_mfma_f32_16x16x32_bf16 v[106:109], v[150:153], v[184:187], v[106:109]
	v_mfma_f32_16x16x32_bf16 v[126:129], v[146:149], v[162:165], v[126:129]
	v_mfma_f32_16x16x32_bf16 v[122:125], v[154:157], v[162:165], v[122:125]
	v_mfma_f32_16x16x32_bf16 v[118:121], v[146:149], v[172:175], v[118:121]
	v_mfma_f32_16x16x32_bf16 v[114:117], v[154:157], v[172:175], v[114:117]
	v_mfma_f32_16x16x32_bf16 v[90:93], v[146:149], v[180:183], v[90:93]
	v_mfma_f32_16x16x32_bf16 v[110:113], v[154:157], v[180:183], v[110:113]
	v_mfma_f32_16x16x32_bf16 v[86:89], v[146:149], v[188:191], v[86:89]
	v_mfma_f32_16x16x32_bf16 v[106:109], v[154:157], v[188:191], v[106:109]
	s_setprio 0
	s_barrier
	s_add_i32 s22, 0, 0x1c000
	s_add_i32 s23, s51, s29
	v_add_u32_e32 v0, s22, v171
	v_lshl_add_u64 v[208:209], v[208:209], 0, s[86:87]
	s_mov_b32 m0, s23
	ds_read_b128 v[192:195], v0
	ds_read_b128 v[196:199], v0 offset:1024
	ds_read_b128 v[200:203], v0 offset:2048
	ds_read_b128 v[204:207], v0 offset:3072
	global_load_lds_dwordx4 v[208:209], off
	v_lshl_add_u64 v[208:209], v[210:211], 0, s[86:87]
	s_add_i32 m0, s23, 0x2000
	s_nop 0
	global_load_lds_dwordx4 v[208:209], off
	s_barrier
	s_waitcnt lgkmcnt(0)
	s_setprio 1
	s_waitcnt lgkmcnt(0)
	v_mfma_f32_16x16x32_bf16 v[62:65], v[192:195], v[158:161], v[62:65]
	v_mfma_f32_16x16x32_bf16 v[58:61], v[200:203], v[158:161], v[58:61]
	v_mfma_f32_16x16x32_bf16 v[54:57], v[192:195], v[166:169], v[54:57]
	v_mfma_f32_16x16x32_bf16 v[50:53], v[200:203], v[166:169], v[50:53]
	v_mfma_f32_16x16x32_bf16 v[26:29], v[192:195], v[176:179], v[26:29]
	v_mfma_f32_16x16x32_bf16 v[46:49], v[200:203], v[176:179], v[46:49]
	v_mfma_f32_16x16x32_bf16 v[22:25], v[192:195], v[184:187], v[22:25]
	v_mfma_f32_16x16x32_bf16 v[42:45], v[200:203], v[184:187], v[42:45]
	v_mfma_f32_16x16x32_bf16 v[62:65], v[196:199], v[162:165], v[62:65]
	v_mfma_f32_16x16x32_bf16 v[58:61], v[204:207], v[162:165], v[58:61]
	v_mfma_f32_16x16x32_bf16 v[54:57], v[196:199], v[172:175], v[54:57]
	v_mfma_f32_16x16x32_bf16 v[50:53], v[204:207], v[172:175], v[50:53]
	v_mfma_f32_16x16x32_bf16 v[26:29], v[196:199], v[180:183], v[26:29]
	v_mfma_f32_16x16x32_bf16 v[46:49], v[204:207], v[180:183], v[46:49]
	v_mfma_f32_16x16x32_bf16 v[22:25], v[196:199], v[188:191], v[22:25]
	v_mfma_f32_16x16x32_bf16 v[42:45], v[204:207], v[188:191], v[42:45]
	s_setprio 0
	s_mov_b32 m0, s42
	v_lshl_add_u64 v[208:209], v[212:213], 0, s[86:87]
	s_barrier
	ds_read_b128 v[158:161], v232 offset:49152
	ds_read_b128 v[162:165], v232 offset:50176
	ds_read_b128 v[166:169], v232 offset:51200
	ds_read_b128 v[172:175], v232 offset:52224
	ds_read_b128 v[176:179], v232 offset:53248
	ds_read_b128 v[180:183], v232 offset:54272
	ds_read_b128 v[184:187], v232 offset:55296
	ds_read_b128 v[188:191], v232 offset:56320
	global_load_lds_dwordx4 v[208:209], off
	v_lshl_add_u64 v[208:209], v[214:215], 0, s[86:87]
	s_mov_b32 m0, s43
	s_nop 0
	global_load_lds_dwordx4 v[208:209], off
	s_barrier
; __device__ __forceinline__ unsigned cvt_pk_bf16(float lo, float hi) { unsigned r; asm volatile("v_cvt_pk_bf16_f32 %0, %1, %2" : "=v"(r) : "v"(lo), "v"(hi)); return r; }
; #define PG8_WAIT_V(n) asm volatile("s_waitcnt vmcnt(" #n ")" ::: "memory")
; template <class Epi>
; __device__ __forceinline__ void gemm_phase(LAS unsigned char* lds, const Gemm g, const StaticOrder& S_in, const Epi& E, int sw) {
;     ...
;             PG8_WAIT_V(6); PG8_BAR; PG8_MMA(1, 1, At, B1); PG8_BAR;
;             PG8_LDB(B0, 1, 0); PG8_SCHED; PG8_LDA(At, 1, 0); PG8_STAGE(PG8_SA(0, 1), a2 + hstepA, voffA);
;             PG8_WAIT_L(8); PG8_BAR; PG8_WAIT_L(0); PG8_MMA(0, 0, At, B0); PG8_BAR; PG8_SCHED;
;             PG8_LDB(B1, 1, 1); PG8_STAGE(PG8_SB(1, 0), b3, voffB);
;             PG8_BAR; PG8_WAIT_L(0); PG8_MMA(0, 1, At, B1); PG8_BAR;
;             PG8_LDA(At, 1, 1); PG8_STAGE(PG8_SA(1, 0), a3, voffA);
;             PG8_BAR; PG8_WAIT_L(0); PG8_MMA(1, 0, At, B0); PG8_BAR; PG8_SCHED;
;             PG8_STAGE(PG8_SB(1, 1), b3 + hstepB, voffB);
;             PG8_WAIT_V(6); PG8_BAR; PG8_MMA(1, 1, At, B1); PG8_BAR;
;     EPI_ZERO_INIT
;     __device__ __forceinline__ void operator()(AccRef acc, const Unit& u, int sw) const {
;         const int tid_ = ltid(sw), lane_ = tid_ & 63, wr = sw >> 2, wc = sw & 3, fr = lane_ & 15, fq = lane_ >> 4;
;         const int row0 = u.pm * BM + wr * 64 + fr, col0 = u.pn * BM + wc * 32 + 8 * fq;
; #pragma unroll
;         for (int bj = 0; bj < 2; ++bj) {
;             float cs[2][4], cq[2][4];
; #pragma unroll
;             for (int n = 0; n < 2; ++n)
; #pragma unroll
;                 for (int j = 0; j < 4; ++j) { cs[n][j] = 0.f; cq[n][j] = 0.f; }
; #pragma unroll
;             for (int ai = 0; ai < 2; ++ai)
; #pragma unroll
;                 for (int m = 0; m < 4; ++m) { bf16_t* rowp = Vt + ((size_t)(2 * u.pn + bj) * E + (row0 + ai * HALF + m * 16)) * 128 + wc * 32 + 8 * fq;
;                     f32x4 v0 = acc[ai][bj][m][0], v1 = acc[ai][bj][m][1];
; #pragma unroll
;                     for (int j = 0; j < 4; ++j) { v0[j] = fgelu(v0[j]); v1[j] = fgelu(v1[j]);
;                         cs[0][j] += v0[j]; cq[0][j] += v0[j] * v0[j]; cs[1][j] += v1[j]; cq[1][j] += v1[j] * v1[j]; }
;                     u32x4 w; w.x = cvt_pk_bf16(v0[0], v0[1]); w.y = cvt_pk_bf16(v0[2], v0[3]); w.z = cvt_pk_bf16(v1[0], v1[1]); w.w = cvt_pk_bf16(v1[2], v1[3]);
	s_waitcnt lgkmcnt(0)
	s_setprio 1
	s_waitcnt lgkmcnt(0)
	v_mfma_f32_16x16x32_bf16 v[78:81], v[142:145], v[158:161], v[78:81]
	v_mfma_f32_16x16x32_bf16 v[102:105], v[150:153], v[158:161], v[102:105]
	v_mfma_f32_16x16x32_bf16 v[74:77], v[142:145], v[166:169], v[74:77]
	v_mfma_f32_16x16x32_bf16 v[98:101], v[150:153], v[166:169], v[98:101]
	v_mfma_f32_16x16x32_bf16 v[70:73], v[142:145], v[176:179], v[70:73]
	v_mfma_f32_16x16x32_bf16 v[94:97], v[150:153], v[176:179], v[94:97]
	v_mfma_f32_16x16x32_bf16 v[66:69], v[142:145], v[184:187], v[66:69]
	v_mfma_f32_16x16x32_bf16 v[82:85], v[150:153], v[184:187], v[82:85]
	v_mfma_f32_16x16x32_bf16 v[78:81], v[146:149], v[162:165], v[78:81]
	v_mfma_f32_16x16x32_bf16 v[102:105], v[154:157], v[162:165], v[102:105]
	v_mfma_f32_16x16x32_bf16 v[74:77], v[146:149], v[172:175], v[74:77]
	v_mfma_f32_16x16x32_bf16 v[98:101], v[154:157], v[172:175], v[98:101]
	v_mfma_f32_16x16x32_bf16 v[70:73], v[146:149], v[180:183], v[70:73]
	v_mfma_f32_16x16x32_bf16 v[94:97], v[154:157], v[180:183], v[94:97]
	v_mfma_f32_16x16x32_bf16 v[66:69], v[146:149], v[188:191], v[66:69]
	v_mfma_f32_16x16x32_bf16 v[82:85], v[154:157], v[188:191], v[82:85]
	s_setprio 0
	s_barrier
	s_add_u32 s20, s20, 0x40080
	s_addc_u32 s21, s21, 0
	s_add_i32 s22, s22, s29
	v_lshl_add_u64 v[142:143], s[20:21], 0, v[132:133]
	s_mov_b32 m0, s22
	s_nop 0
	global_load_lds_dwordx4 v[142:143], off
	v_lshl_add_u64 v[142:143], s[20:21], 0, v[136:137]
	s_add_i32 m0, s22, 0x2000
	s_nop 0
	global_load_lds_dwordx4 v[142:143], off
	s_waitcnt vmcnt(6)
	s_barrier
	s_setprio 1
	v_mfma_f32_16x16x32_bf16 v[14:17], v[192:195], v[158:161], v[14:17]
	v_mfma_f32_16x16x32_bf16 v[38:41], v[200:203], v[158:161], v[38:41]
	v_mfma_f32_16x16x32_bf16 v[10:13], v[192:195], v[166:169], v[10:13]
	v_mfma_f32_16x16x32_bf16 v[34:37], v[200:203], v[166:169], v[34:37]
	v_mfma_f32_16x16x32_bf16 v[6:9], v[192:195], v[176:179], v[6:9]
	v_mfma_f32_16x16x32_bf16 v[30:33], v[200:203], v[176:179], v[30:33]
	v_mfma_f32_16x16x32_bf16 v[2:5], v[192:195], v[184:187], v[2:5]
	v_mfma_f32_16x16x32_bf16 v[18:21], v[200:203], v[184:187], v[18:21]
	v_mfma_f32_16x16x32_bf16 v[14:17], v[196:199], v[162:165], v[14:17]
	v_mfma_f32_16x16x32_bf16 v[38:41], v[204:207], v[162:165], v[38:41]
	v_mfma_f32_16x16x32_bf16 v[10:13], v[196:199], v[172:175], v[10:13]
	v_mfma_f32_16x16x32_bf16 v[34:37], v[204:207], v[172:175], v[34:37]
	v_mfma_f32_16x16x32_bf16 v[6:9], v[196:199], v[180:183], v[6:9]
	v_mfma_f32_16x16x32_bf16 v[30:33], v[204:207], v[180:183], v[30:33]
	v_mfma_f32_16x16x32_bf16 v[2:5], v[196:199], v[188:191], v[2:5]
	v_mfma_f32_16x16x32_bf16 v[18:21], v[204:207], v[188:191], v[18:21]
	s_setprio 0
	s_add_i32 s50, s50, 2
	s_add_u32 s0, s0, 0x100
	s_addc_u32 s1, s1, 0
	s_add_u32 s48, s48, 0x100
	s_addc_u32 s49, s49, 0
	s_cmp_gt_u32 s50, 13
	s_barrier
	s_cbranch_scc0 .LBB0_771
	v_readlane_b32 s7, v255, 6
	v_readlane_b32 s1, v255, 7
	v_mbcnt_lo_u32_b32 v223, -1, 0
	v_mbcnt_hi_u32_b32 v223, -1, v223
	v_lshl_add_u32 v223, s75, 6, v223
	s_nop 3
	s_lshl_b32 s0, s18, 8
	s_add_i32 s0, s0, s1
	v_and_b32_e32 v220, 15, v223
	v_lshrrev_b32_e32 v221, 1, v223
	v_and_b32_e32 v221, 24, v221
	v_or_b32_e32 v223, s0, v220
	v_lshlrev_b32_e32 v212, 8, v223
	v_lshl_add_u32 v212, v221, 1, v212
	v_add_u32_e32 v212, s90, v212
	s_lshl_b32 s0, s18, 1
	s_add_i32 s0, s0, s7
	s_ashr_i32 s1, s0, 31
	s_lshl_b64 s[0:1], s[0:1], 18
	s_add_u32 s0, s40, s0
	s_addc_u32 s1, s41, s1
	s_lshl_b32 s18, s16, 1
	s_ashr_i32 s19, s18, 31
	s_lshl_b64 s[18:19], s[18:19], 19
	s_add_u32 s18, s38, s18
	s_addc_u32 s19, s39, s19
	s_add_u32 s20, s18, 0x80000
	s_addc_u32 s21, s19, 0
	s_lshl_b32 s7, s16, 8
	s_or_b32 s7, s7, s85
	v_or_b32_e32 v222, s7, v221
	v_lshlrev_b32_e32 v222, 3, v222
	s_mov_b64 s[16:17], s[0:1]
	s_mov_b32 s0, 0xbdd2d3e7
	v_mov_b32_e32 v224, s84
	v_cmp_eq_u32_e32 vcc, 0, v220
	v_add_u32_e32 v213, 0x1000, v212
	v_add_u32_e32 v214, 0x2000, v212
	v_add_u32_e32 v215, 0x3000, v212
	v_add_u32_e32 v216, 0x8000, v212
	v_add_u32_e32 v217, 0x9000, v212
	v_add_u32_e32 v218, 0xa000, v212
	v_add_u32_e32 v219, 0xb000, v212
	v_mov_b64 v[172:173], 0
	v_mov_b64 v[174:175], 0
	v_mov_b64 v[176:177], 0
	v_mov_b64 v[178:179], 0
	v_mov_b64 v[180:181], 0
	v_mov_b64 v[182:183], 0
	v_mov_b64 v[184:185], 0
	v_mov_b64 v[186:187], 0
	v_pk_mul_f32 v[188:189], v[126:127], v[126:127]
	v_pk_mul_f32 v[190:191], v[128:129], v[128:129]
	v_pk_mul_f32 v[192:193], v[122:123], v[122:123]
	v_pk_mul_f32 v[194:195], v[124:125], v[124:125]
	v_pk_fma_f32 v[188:189], v[188:189], s[0:1], v[224:225] op_sel_hi:[1,0,0]
	v_pk_fma_f32 v[190:191], v[190:191], s[0:1], v[224:225] op_sel_hi:[1,0,0]
	v_pk_fma_f32 v[192:193], v[192:193], s[0:1], v[224:225] op_sel_hi:[1,0,0]
	v_pk_fma_f32 v[194:195], v[194:195], s[0:1], v[224:225] op_sel_hi:[1,0,0]
	v_pk_mul_f32 v[188:189], v[188:189], v[126:127]
	v_pk_mul_f32 v[190:191], v[190:191], v[128:129]
	v_pk_mul_f32 v[192:193], v[192:193], v[122:123]
	v_pk_mul_f32 v[194:195], v[194:195], v[124:125]
	v_exp_f32_e32 v188, v188
	v_exp_f32_e32 v189, v189
	v_exp_f32_e32 v190, v190
	v_exp_f32_e32 v191, v191
	v_exp_f32_e32 v192, v192
	v_exp_f32_e32 v193, v193
	v_exp_f32_e32 v194, v194
	v_exp_f32_e32 v195, v195
	v_pk_add_f32 v[188:189], v[188:189], 1.0 op_sel_hi:[1,0]
	v_pk_add_f32 v[190:191], v[190:191], 1.0 op_sel_hi:[1,0]
	v_pk_add_f32 v[192:193], v[192:193], 1.0 op_sel_hi:[1,0]
	v_pk_add_f32 v[194:195], v[194:195], 1.0 op_sel_hi:[1,0]
	v_rcp_f32_e32 v188, v188
	v_rcp_f32_e32 v189, v189
	v_rcp_f32_e32 v190, v190
	v_rcp_f32_e32 v191, v191
	v_rcp_f32_e32 v192, v192
	v_rcp_f32_e32 v193, v193
	v_rcp_f32_e32 v194, v194
	v_rcp_f32_e32 v195, v195
	v_pk_mul_f32 v[196:197], v[126:127], v[188:189]
; __device__ __forceinline__ unsigned cvt_pk_bf16(float lo, float hi) { unsigned r; asm volatile("v_cvt_pk_bf16_f32 %0, %1, %2" : "=v"(r) : "v"(lo), "v"(hi)); return r; }
; __device__ __forceinline__ float fgelu(float x) { const float u = x * (1.0f + 0.044715f * x * x); return x * fsigmoid(1.59576912f * u); }
;     EPI_ZERO_INIT
;     __device__ __forceinline__ void operator()(AccRef acc, const Unit& u, int sw) const {
;     ...
;                 for (int m = 0; m < 4; ++m) { bf16_t* rowp = Vt + ((size_t)(2 * u.pn + bj) * E + (row0 + ai * HALF + m * 16)) * 128 + wc * 32 + 8 * fq;
;                     f32x4 v0 = acc[ai][bj][m][0], v1 = acc[ai][bj][m][1];
; #pragma unroll
;                     for (int j = 0; j < 4; ++j) { v0[j] = fgelu(v0[j]); v1[j] = fgelu(v1[j]);
;                         cs[0][j] += v0[j]; cq[0][j] += v0[j] * v0[j]; cs[1][j] += v1[j]; cq[1][j] += v1[j] * v1[j]; }
;                     u32x4 w; w.x = cvt_pk_bf16(v0[0], v0[1]); w.y = cvt_pk_bf16(v0[2], v0[3]); w.z = cvt_pk_bf16(v1[0], v1[1]); w.w = cvt_pk_bf16(v1[2], v1[3]);
;                     *(u32x4*)rowp = w; }
	v_pk_mul_f32 v[198:199], v[128:129], v[190:191]
	v_pk_mul_f32 v[200:201], v[122:123], v[192:193]
	v_pk_mul_f32 v[202:203], v[124:125], v[194:195]
	v_pk_add_f32 v[172:173], v[172:173], v[196:197]
	v_pk_add_f32 v[174:175], v[174:175], v[198:199]
	v_pk_add_f32 v[176:177], v[176:177], v[200:201]
	v_pk_add_f32 v[178:179], v[178:179], v[202:203]
	v_pk_fma_f32 v[180:181], v[196:197], v[196:197], v[180:181]
	v_pk_fma_f32 v[182:183], v[198:199], v[198:199], v[182:183]
	v_pk_fma_f32 v[184:185], v[200:201], v[200:201], v[184:185]
	v_pk_fma_f32 v[186:187], v[202:203], v[202:203], v[186:187]
	v_cvt_pk_bf16_f32 v204, v196, v197
	v_cvt_pk_bf16_f32 v205, v198, v199
	v_cvt_pk_bf16_f32 v206, v200, v201
	v_cvt_pk_bf16_f32 v207, v202, v203
	global_store_dwordx4 v212, v[204:207], s[18:19]
	v_pk_mul_f32 v[188:189], v[118:119], v[118:119]
	v_pk_mul_f32 v[190:191], v[120:121], v[120:121]
	v_pk_mul_f32 v[192:193], v[114:115], v[114:115]
	v_pk_mul_f32 v[194:195], v[116:117], v[116:117]
	v_pk_fma_f32 v[188:189], v[188:189], s[0:1], v[224:225] op_sel_hi:[1,0,0]
	v_pk_fma_f32 v[190:191], v[190:191], s[0:1], v[224:225] op_sel_hi:[1,0,0]
	v_pk_fma_f32 v[192:193], v[192:193], s[0:1], v[224:225] op_sel_hi:[1,0,0]
	v_pk_fma_f32 v[194:195], v[194:195], s[0:1], v[224:225] op_sel_hi:[1,0,0]
	v_pk_mul_f32 v[188:189], v[188:189], v[118:119]
	v_pk_mul_f32 v[190:191], v[190:191], v[120:121]
	v_pk_mul_f32 v[192:193], v[192:193], v[114:115]
	v_pk_mul_f32 v[194:195], v[194:195], v[116:117]
	v_exp_f32_e32 v188, v188
	v_exp_f32_e32 v189, v189
	v_exp_f32_e32 v190, v190
	v_exp_f32_e32 v191, v191
	v_exp_f32_e32 v192, v192
	v_exp_f32_e32 v193, v193
	v_exp_f32_e32 v194, v194
	v_exp_f32_e32 v195, v195
	v_pk_add_f32 v[188:189], v[188:189], 1.0 op_sel_hi:[1,0]
	v_pk_add_f32 v[190:191], v[190:191], 1.0 op_sel_hi:[1,0]
	v_pk_add_f32 v[192:193], v[192:193], 1.0 op_sel_hi:[1,0]
	v_pk_add_f32 v[194:195], v[194:195], 1.0 op_sel_hi:[1,0]
	v_rcp_f32_e32 v188, v188
	v_rcp_f32_e32 v189, v189
	v_rcp_f32_e32 v190, v190
	v_rcp_f32_e32 v191, v191
	v_rcp_f32_e32 v192, v192
	v_rcp_f32_e32 v193, v193
	v_rcp_f32_e32 v194, v194
	v_rcp_f32_e32 v195, v195
	v_pk_mul_f32 v[196:197], v[118:119], v[188:189]
	v_pk_mul_f32 v[198:199], v[120:121], v[190:191]
	v_pk_mul_f32 v[200:201], v[114:115], v[192:193]
	v_pk_mul_f32 v[202:203], v[116:117], v[194:195]
	v_pk_add_f32 v[172:173], v[172:173], v[196:197]
	v_pk_add_f32 v[174:175], v[174:175], v[198:199]
	v_pk_add_f32 v[176:177], v[176:177], v[200:201]
	v_pk_add_f32 v[178:179], v[178:179], v[202:203]
	v_pk_fma_f32 v[180:181], v[196:197], v[196:197], v[180:181]
	v_pk_fma_f32 v[182:183], v[198:199], v[198:199], v[182:183]
	v_pk_fma_f32 v[184:185], v[200:201], v[200:201], v[184:185]
	v_pk_fma_f32 v[186:187], v[202:203], v[202:203], v[186:187]
	v_cvt_pk_bf16_f32 v208, v196, v197
	v_cvt_pk_bf16_f32 v209, v198, v199
	v_cvt_pk_bf16_f32 v210, v200, v201
	v_cvt_pk_bf16_f32 v211, v202, v203
	global_store_dwordx4 v213, v[208:211], s[18:19]
	v_pk_mul_f32 v[188:189], v[90:91], v[90:91]
	v_pk_mul_f32 v[190:191], v[92:93], v[92:93]
	v_pk_mul_f32 v[192:193], v[110:111], v[110:111]
	v_pk_mul_f32 v[194:195], v[112:113], v[112:113]
	v_pk_fma_f32 v[188:189], v[188:189], s[0:1], v[224:225] op_sel_hi:[1,0,0]
	v_pk_fma_f32 v[190:191], v[190:191], s[0:1], v[224:225] op_sel_hi:[1,0,0]
	v_pk_fma_f32 v[192:193], v[192:193], s[0:1], v[224:225] op_sel_hi:[1,0,0]
	v_pk_fma_f32 v[194:195], v[194:195], s[0:1], v[224:225] op_sel_hi:[1,0,0]
	v_pk_mul_f32 v[188:189], v[188:189], v[90:91]
	v_pk_mul_f32 v[190:191], v[190:191], v[92:93]
	v_pk_mul_f32 v[192:193], v[192:193], v[110:111]
	v_pk_mul_f32 v[194:195], v[194:195], v[112:113]
	v_exp_f32_e32 v188, v188
	v_exp_f32_e32 v189, v189
	v_exp_f32_e32 v190, v190
	v_exp_f32_e32 v191, v191
	v_exp_f32_e32 v192, v192
	v_exp_f32_e32 v193, v193
	v_exp_f32_e32 v194, v194
	v_exp_f32_e32 v195, v195
	v_pk_add_f32 v[188:189], v[188:189], 1.0 op_sel_hi:[1,0]
	v_pk_add_f32 v[190:191], v[190:191], 1.0 op_sel_hi:[1,0]
	v_pk_add_f32 v[192:193], v[192:193], 1.0 op_sel_hi:[1,0]
	v_pk_add_f32 v[194:195], v[194:195], 1.0 op_sel_hi:[1,0]
	v_rcp_f32_e32 v188, v188
	v_rcp_f32_e32 v189, v189
	v_rcp_f32_e32 v190, v190
	v_rcp_f32_e32 v191, v191
	v_rcp_f32_e32 v192, v192
	v_rcp_f32_e32 v193, v193
	v_rcp_f32_e32 v194, v194
	v_rcp_f32_e32 v195, v195
	v_pk_mul_f32 v[196:197], v[90:91], v[188:189]
	v_pk_mul_f32 v[198:199], v[92:93], v[190:191]
	v_pk_mul_f32 v[200:201], v[110:111], v[192:193]
	v_pk_mul_f32 v[202:203], v[112:113], v[194:195]
	v_pk_add_f32 v[172:173], v[172:173], v[196:197]
	v_pk_add_f32 v[174:175], v[174:175], v[198:199]
	v_pk_add_f32 v[176:177], v[176:177], v[200:201]
	v_pk_add_f32 v[178:179], v[178:179], v[202:203]
	v_pk_fma_f32 v[180:181], v[196:197], v[196:197], v[180:181]
	v_pk_fma_f32 v[182:183], v[198:199], v[198:199], v[182:183]
	v_pk_fma_f32 v[184:185], v[200:201], v[200:201], v[184:185]
	v_pk_fma_f32 v[186:187], v[202:203], v[202:203], v[186:187]
	v_cvt_pk_bf16_f32 v204, v196, v197
	v_cvt_pk_bf16_f32 v205, v198, v199
	v_cvt_pk_bf16_f32 v206, v200, v201
	v_cvt_pk_bf16_f32 v207, v202, v203
	global_store_dwordx4 v214, v[204:207], s[18:19]
	v_pk_mul_f32 v[188:189], v[86:87], v[86:87]
	v_pk_mul_f32 v[190:191], v[88:89], v[88:89]
	v_pk_mul_f32 v[192:193], v[106:107], v[106:107]
	v_pk_mul_f32 v[194:195], v[108:109], v[108:109]
	v_pk_fma_f32 v[188:189], v[188:189], s[0:1], v[224:225] op_sel_hi:[1,0,0]
	v_pk_fma_f32 v[190:191], v[190:191], s[0:1], v[224:225] op_sel_hi:[1,0,0]
	v_pk_fma_f32 v[192:193], v[192:193], s[0:1], v[224:225] op_sel_hi:[1,0,0]
	v_pk_fma_f32 v[194:195], v[194:195], s[0:1], v[224:225] op_sel_hi:[1,0,0]
	v_pk_mul_f32 v[188:189], v[188:189], v[86:87]
; __device__ __forceinline__ unsigned cvt_pk_bf16(float lo, float hi) { unsigned r; asm volatile("v_cvt_pk_bf16_f32 %0, %1, %2" : "=v"(r) : "v"(lo), "v"(hi)); return r; }
; __device__ __forceinline__ float fgelu(float x) { const float u = x * (1.0f + 0.044715f * x * x); return x * fsigmoid(1.59576912f * u); }
;     EPI_ZERO_INIT
;     __device__ __forceinline__ void operator()(AccRef acc, const Unit& u, int sw) const {
;     ...
;                 for (int m = 0; m < 4; ++m) { bf16_t* rowp = Vt + ((size_t)(2 * u.pn + bj) * E + (row0 + ai * HALF + m * 16)) * 128 + wc * 32 + 8 * fq;
;                     f32x4 v0 = acc[ai][bj][m][0], v1 = acc[ai][bj][m][1];
; #pragma unroll
;                     for (int j = 0; j < 4; ++j) { v0[j] = fgelu(v0[j]); v1[j] = fgelu(v1[j]);
;                         cs[0][j] += v0[j]; cq[0][j] += v0[j] * v0[j]; cs[1][j] += v1[j]; cq[1][j] += v1[j] * v1[j]; }
;                     u32x4 w; w.x = cvt_pk_bf16(v0[0], v0[1]); w.y = cvt_pk_bf16(v0[2], v0[3]); w.z = cvt_pk_bf16(v1[0], v1[1]); w.w = cvt_pk_bf16(v1[2], v1[3]);
;                     *(u32x4*)rowp = w; }
	v_pk_mul_f32 v[190:191], v[190:191], v[88:89]
	v_pk_mul_f32 v[192:193], v[192:193], v[106:107]
	v_pk_mul_f32 v[194:195], v[194:195], v[108:109]
	v_exp_f32_e32 v188, v188
	v_exp_f32_e32 v189, v189
	v_exp_f32_e32 v190, v190
	v_exp_f32_e32 v191, v191
	v_exp_f32_e32 v192, v192
	v_exp_f32_e32 v193, v193
	v_exp_f32_e32 v194, v194
	v_exp_f32_e32 v195, v195
	v_pk_add_f32 v[188:189], v[188:189], 1.0 op_sel_hi:[1,0]
	v_pk_add_f32 v[190:191], v[190:191], 1.0 op_sel_hi:[1,0]
	v_pk_add_f32 v[192:193], v[192:193], 1.0 op_sel_hi:[1,0]
	v_pk_add_f32 v[194:195], v[194:195], 1.0 op_sel_hi:[1,0]
	v_rcp_f32_e32 v188, v188
	v_rcp_f32_e32 v189, v189
	v_rcp_f32_e32 v190, v190
	v_rcp_f32_e32 v191, v191
	v_rcp_f32_e32 v192, v192
	v_rcp_f32_e32 v193, v193
	v_rcp_f32_e32 v194, v194
	v_rcp_f32_e32 v195, v195
	v_pk_mul_f32 v[196:197], v[86:87], v[188:189]
	v_pk_mul_f32 v[198:199], v[88:89], v[190:191]
	v_pk_mul_f32 v[200:201], v[106:107], v[192:193]
	v_pk_mul_f32 v[202:203], v[108:109], v[194:195]
	v_pk_add_f32 v[172:173], v[172:173], v[196:197]
	v_pk_add_f32 v[174:175], v[174:175], v[198:199]
	v_pk_add_f32 v[176:177], v[176:177], v[200:201]
	v_pk_add_f32 v[178:179], v[178:179], v[202:203]
	v_pk_fma_f32 v[180:181], v[196:197], v[196:197], v[180:181]
	v_pk_fma_f32 v[182:183], v[198:199], v[198:199], v[182:183]
	v_pk_fma_f32 v[184:185], v[200:201], v[200:201], v[184:185]
	v_pk_fma_f32 v[186:187], v[202:203], v[202:203], v[186:187]
	v_cvt_pk_bf16_f32 v208, v196, v197
	v_cvt_pk_bf16_f32 v209, v198, v199
	v_cvt_pk_bf16_f32 v210, v200, v201
	v_cvt_pk_bf16_f32 v211, v202, v203
	global_store_dwordx4 v215, v[208:211], s[18:19]
	v_pk_mul_f32 v[188:189], v[78:79], v[78:79]
	v_pk_mul_f32 v[190:191], v[80:81], v[80:81]
	v_pk_mul_f32 v[192:193], v[102:103], v[102:103]
	v_pk_mul_f32 v[194:195], v[104:105], v[104:105]
	v_pk_fma_f32 v[188:189], v[188:189], s[0:1], v[224:225] op_sel_hi:[1,0,0]
	v_pk_fma_f32 v[190:191], v[190:191], s[0:1], v[224:225] op_sel_hi:[1,0,0]
	v_pk_fma_f32 v[192:193], v[192:193], s[0:1], v[224:225] op_sel_hi:[1,0,0]
	v_pk_fma_f32 v[194:195], v[194:195], s[0:1], v[224:225] op_sel_hi:[1,0,0]
	v_pk_mul_f32 v[188:189], v[188:189], v[78:79]
	v_pk_mul_f32 v[190:191], v[190:191], v[80:81]
	v_pk_mul_f32 v[192:193], v[192:193], v[102:103]
	v_pk_mul_f32 v[194:195], v[194:195], v[104:105]
	v_exp_f32_e32 v188, v188
	v_exp_f32_e32 v189, v189
	v_exp_f32_e32 v190, v190
	v_exp_f32_e32 v191, v191
	v_exp_f32_e32 v192, v192
	v_exp_f32_e32 v193, v193
	v_exp_f32_e32 v194, v194
	v_exp_f32_e32 v195, v195
	v_pk_add_f32 v[188:189], v[188:189], 1.0 op_sel_hi:[1,0]
	v_pk_add_f32 v[190:191], v[190:191], 1.0 op_sel_hi:[1,0]
	v_pk_add_f32 v[192:193], v[192:193], 1.0 op_sel_hi:[1,0]
	v_pk_add_f32 v[194:195], v[194:195], 1.0 op_sel_hi:[1,0]
	v_rcp_f32_e32 v188, v188
	v_rcp_f32_e32 v189, v189
	v_rcp_f32_e32 v190, v190
	v_rcp_f32_e32 v191, v191
	v_rcp_f32_e32 v192, v192
	v_rcp_f32_e32 v193, v193
	v_rcp_f32_e32 v194, v194
	v_rcp_f32_e32 v195, v195
	v_pk_mul_f32 v[196:197], v[78:79], v[188:189]
	v_pk_mul_f32 v[198:199], v[80:81], v[190:191]
	v_pk_mul_f32 v[200:201], v[102:103], v[192:193]
	v_pk_mul_f32 v[202:203], v[104:105], v[194:195]
	v_pk_add_f32 v[172:173], v[172:173], v[196:197]
	v_pk_add_f32 v[174:175], v[174:175], v[198:199]
	v_pk_add_f32 v[176:177], v[176:177], v[200:201]
	v_pk_add_f32 v[178:179], v[178:179], v[202:203]
	v_pk_fma_f32 v[180:181], v[196:197], v[196:197], v[180:181]
	v_pk_fma_f32 v[182:183], v[198:199], v[198:199], v[182:183]
	v_pk_fma_f32 v[184:185], v[200:201], v[200:201], v[184:185]
	v_pk_fma_f32 v[186:187], v[202:203], v[202:203], v[186:187]
	v_cvt_pk_bf16_f32 v204, v196, v197
	v_cvt_pk_bf16_f32 v205, v198, v199
	v_cvt_pk_bf16_f32 v206, v200, v201
	v_cvt_pk_bf16_f32 v207, v202, v203
	global_store_dwordx4 v216, v[204:207], s[18:19]
	v_pk_mul_f32 v[188:189], v[74:75], v[74:75]
	v_pk_mul_f32 v[190:191], v[76:77], v[76:77]
	v_pk_mul_f32 v[192:193], v[98:99], v[98:99]
	v_pk_mul_f32 v[194:195], v[100:101], v[100:101]
	v_pk_fma_f32 v[188:189], v[188:189], s[0:1], v[224:225] op_sel_hi:[1,0,0]
	v_pk_fma_f32 v[190:191], v[190:191], s[0:1], v[224:225] op_sel_hi:[1,0,0]
	v_pk_fma_f32 v[192:193], v[192:193], s[0:1], v[224:225] op_sel_hi:[1,0,0]
	v_pk_fma_f32 v[194:195], v[194:195], s[0:1], v[224:225] op_sel_hi:[1,0,0]
	v_pk_mul_f32 v[188:189], v[188:189], v[74:75]
	v_pk_mul_f32 v[190:191], v[190:191], v[76:77]
	v_pk_mul_f32 v[192:193], v[192:193], v[98:99]
	v_pk_mul_f32 v[194:195], v[194:195], v[100:101]
	v_exp_f32_e32 v188, v188
	v_exp_f32_e32 v189, v189
	v_exp_f32_e32 v190, v190
	v_exp_f32_e32 v191, v191
	v_exp_f32_e32 v192, v192
	v_exp_f32_e32 v193, v193
	v_exp_f32_e32 v194, v194
	v_exp_f32_e32 v195, v195
	v_pk_add_f32 v[188:189], v[188:189], 1.0 op_sel_hi:[1,0]
	v_pk_add_f32 v[190:191], v[190:191], 1.0 op_sel_hi:[1,0]
	v_pk_add_f32 v[192:193], v[192:193], 1.0 op_sel_hi:[1,0]
	v_pk_add_f32 v[194:195], v[194:195], 1.0 op_sel_hi:[1,0]
	v_rcp_f32_e32 v188, v188
	v_rcp_f32_e32 v189, v189
	v_rcp_f32_e32 v190, v190
	v_rcp_f32_e32 v191, v191
	v_rcp_f32_e32 v192, v192
	v_rcp_f32_e32 v193, v193
	v_rcp_f32_e32 v194, v194
	v_rcp_f32_e32 v195, v195
	v_pk_mul_f32 v[196:197], v[74:75], v[188:189]
	v_pk_mul_f32 v[198:199], v[76:77], v[190:191]
	v_pk_mul_f32 v[200:201], v[98:99], v[192:193]
	v_pk_mul_f32 v[202:203], v[100:101], v[194:195]
	v_pk_add_f32 v[172:173], v[172:173], v[196:197]
	v_pk_add_f32 v[174:175], v[174:175], v[198:199]
	v_pk_add_f32 v[176:177], v[176:177], v[200:201]
	v_pk_add_f32 v[178:179], v[178:179], v[202:203]
	v_pk_fma_f32 v[180:181], v[196:197], v[196:197], v[180:181]
	v_pk_fma_f32 v[182:183], v[198:199], v[198:199], v[182:183]
	v_pk_fma_f32 v[184:185], v[200:201], v[200:201], v[184:185]
; __device__ __forceinline__ unsigned cvt_pk_bf16(float lo, float hi) { unsigned r; asm volatile("v_cvt_pk_bf16_f32 %0, %1, %2" : "=v"(r) : "v"(lo), "v"(hi)); return r; }
; __device__ __forceinline__ float fgelu(float x) { const float u = x * (1.0f + 0.044715f * x * x); return x * fsigmoid(1.59576912f * u); }
; template <int K> __device__ __forceinline__ float row_ror(float v) { return __int_as_float(__builtin_amdgcn_update_dpp(0, __float_as_int(v), 0x120 + K, 0xF, 0xF, false)); }
;     EPI_ZERO_INIT
;     __device__ __forceinline__ void operator()(AccRef acc, const Unit& u, int sw) const {
;     ...
;                 for (int m = 0; m < 4; ++m) { bf16_t* rowp = Vt + ((size_t)(2 * u.pn + bj) * E + (row0 + ai * HALF + m * 16)) * 128 + wc * 32 + 8 * fq;
;                     f32x4 v0 = acc[ai][bj][m][0], v1 = acc[ai][bj][m][1];
; #pragma unroll
;                     for (int j = 0; j < 4; ++j) { v0[j] = fgelu(v0[j]); v1[j] = fgelu(v1[j]);
;                         cs[0][j] += v0[j]; cq[0][j] += v0[j] * v0[j]; cs[1][j] += v1[j]; cq[1][j] += v1[j] * v1[j]; }
;                     u32x4 w; w.x = cvt_pk_bf16(v0[0], v0[1]); w.y = cvt_pk_bf16(v0[2], v0[3]); w.z = cvt_pk_bf16(v1[0], v1[1]); w.w = cvt_pk_bf16(v1[2], v1[3]);
;                     *(u32x4*)rowp = w; }
;             f32x2* sp = VSTAT + (size_t)(u.pm * 2 + wr) * M + col0 + bj * HALF;
; #pragma unroll
;             for (int n = 0; n < 2; ++n)
; #pragma unroll
;                 for (int j = 0; j < 4; ++j) { float s = cs[n][j], q = cq[n][j];
;                     s += row_ror<8>(s); q += row_ror<8>(q); s += row_ror<4>(s); q += row_ror<4>(q);
;                     s += row_ror<2>(s); q += row_ror<2>(q); s += row_ror<1>(s); q += row_ror<1>(q);
;                     if (fr == 0) sp[4 * n + j] = (f32x2){s, q}; }
	v_pk_fma_f32 v[186:187], v[202:203], v[202:203], v[186:187]
	v_cvt_pk_bf16_f32 v208, v196, v197
	v_cvt_pk_bf16_f32 v209, v198, v199
	v_cvt_pk_bf16_f32 v210, v200, v201
	v_cvt_pk_bf16_f32 v211, v202, v203
	global_store_dwordx4 v217, v[208:211], s[18:19]
	v_pk_mul_f32 v[188:189], v[70:71], v[70:71]
	v_pk_mul_f32 v[190:191], v[72:73], v[72:73]
	v_pk_mul_f32 v[192:193], v[94:95], v[94:95]
	v_pk_mul_f32 v[194:195], v[96:97], v[96:97]
	v_pk_fma_f32 v[188:189], v[188:189], s[0:1], v[224:225] op_sel_hi:[1,0,0]
	v_pk_fma_f32 v[190:191], v[190:191], s[0:1], v[224:225] op_sel_hi:[1,0,0]
	v_pk_fma_f32 v[192:193], v[192:193], s[0:1], v[224:225] op_sel_hi:[1,0,0]
	v_pk_fma_f32 v[194:195], v[194:195], s[0:1], v[224:225] op_sel_hi:[1,0,0]
	v_pk_mul_f32 v[188:189], v[188:189], v[70:71]
	v_pk_mul_f32 v[190:191], v[190:191], v[72:73]
	v_pk_mul_f32 v[192:193], v[192:193], v[94:95]
	v_pk_mul_f32 v[194:195], v[194:195], v[96:97]
	v_exp_f32_e32 v188, v188
	v_exp_f32_e32 v189, v189
	v_exp_f32_e32 v190, v190
	v_exp_f32_e32 v191, v191
	v_exp_f32_e32 v192, v192
	v_exp_f32_e32 v193, v193
	v_exp_f32_e32 v194, v194
	v_exp_f32_e32 v195, v195
	v_pk_add_f32 v[188:189], v[188:189], 1.0 op_sel_hi:[1,0]
	v_pk_add_f32 v[190:191], v[190:191], 1.0 op_sel_hi:[1,0]
	v_pk_add_f32 v[192:193], v[192:193], 1.0 op_sel_hi:[1,0]
	v_pk_add_f32 v[194:195], v[194:195], 1.0 op_sel_hi:[1,0]
	v_rcp_f32_e32 v188, v188
	v_rcp_f32_e32 v189, v189
	v_rcp_f32_e32 v190, v190
	v_rcp_f32_e32 v191, v191
	v_rcp_f32_e32 v192, v192
	v_rcp_f32_e32 v193, v193
	v_rcp_f32_e32 v194, v194
	v_rcp_f32_e32 v195, v195
	v_pk_mul_f32 v[196:197], v[70:71], v[188:189]
	v_pk_mul_f32 v[198:199], v[72:73], v[190:191]
	v_pk_mul_f32 v[200:201], v[94:95], v[192:193]
	v_pk_mul_f32 v[202:203], v[96:97], v[194:195]
	v_pk_add_f32 v[172:173], v[172:173], v[196:197]
	v_pk_add_f32 v[174:175], v[174:175], v[198:199]
	v_pk_add_f32 v[176:177], v[176:177], v[200:201]
	v_pk_add_f32 v[178:179], v[178:179], v[202:203]
	v_pk_fma_f32 v[180:181], v[196:197], v[196:197], v[180:181]
	v_pk_fma_f32 v[182:183], v[198:199], v[198:199], v[182:183]
	v_pk_fma_f32 v[184:185], v[200:201], v[200:201], v[184:185]
	v_pk_fma_f32 v[186:187], v[202:203], v[202:203], v[186:187]
	v_cvt_pk_bf16_f32 v204, v196, v197
	v_cvt_pk_bf16_f32 v205, v198, v199
	v_cvt_pk_bf16_f32 v206, v200, v201
	v_cvt_pk_bf16_f32 v207, v202, v203
	global_store_dwordx4 v218, v[204:207], s[18:19]
	v_pk_mul_f32 v[188:189], v[66:67], v[66:67]
	v_pk_mul_f32 v[190:191], v[68:69], v[68:69]
	v_pk_mul_f32 v[192:193], v[82:83], v[82:83]
	v_pk_mul_f32 v[194:195], v[84:85], v[84:85]
	v_pk_fma_f32 v[188:189], v[188:189], s[0:1], v[224:225] op_sel_hi:[1,0,0]
	v_pk_fma_f32 v[190:191], v[190:191], s[0:1], v[224:225] op_sel_hi:[1,0,0]
	v_pk_fma_f32 v[192:193], v[192:193], s[0:1], v[224:225] op_sel_hi:[1,0,0]
	v_pk_fma_f32 v[194:195], v[194:195], s[0:1], v[224:225] op_sel_hi:[1,0,0]
	v_pk_mul_f32 v[188:189], v[188:189], v[66:67]
	v_pk_mul_f32 v[190:191], v[190:191], v[68:69]
	v_pk_mul_f32 v[192:193], v[192:193], v[82:83]
	v_pk_mul_f32 v[194:195], v[194:195], v[84:85]
	v_exp_f32_e32 v188, v188
	v_exp_f32_e32 v189, v189
	v_exp_f32_e32 v190, v190
	v_exp_f32_e32 v191, v191
	v_exp_f32_e32 v192, v192
	v_exp_f32_e32 v193, v193
	v_exp_f32_e32 v194, v194
	v_exp_f32_e32 v195, v195
	v_pk_add_f32 v[188:189], v[188:189], 1.0 op_sel_hi:[1,0]
	v_pk_add_f32 v[190:191], v[190:191], 1.0 op_sel_hi:[1,0]
	v_pk_add_f32 v[192:193], v[192:193], 1.0 op_sel_hi:[1,0]
	v_pk_add_f32 v[194:195], v[194:195], 1.0 op_sel_hi:[1,0]
	v_rcp_f32_e32 v188, v188
	v_rcp_f32_e32 v189, v189
	v_rcp_f32_e32 v190, v190
	v_rcp_f32_e32 v191, v191
	v_rcp_f32_e32 v192, v192
	v_rcp_f32_e32 v193, v193
	v_rcp_f32_e32 v194, v194
	v_rcp_f32_e32 v195, v195
	v_pk_mul_f32 v[196:197], v[66:67], v[188:189]
	v_pk_mul_f32 v[198:199], v[68:69], v[190:191]
	v_pk_mul_f32 v[200:201], v[82:83], v[192:193]
	v_pk_mul_f32 v[202:203], v[84:85], v[194:195]
	v_pk_add_f32 v[172:173], v[172:173], v[196:197]
	v_pk_add_f32 v[174:175], v[174:175], v[198:199]
	v_pk_add_f32 v[176:177], v[176:177], v[200:201]
	v_pk_add_f32 v[178:179], v[178:179], v[202:203]
	v_pk_fma_f32 v[180:181], v[196:197], v[196:197], v[180:181]
	v_pk_fma_f32 v[182:183], v[198:199], v[198:199], v[182:183]
	v_pk_fma_f32 v[184:185], v[200:201], v[200:201], v[184:185]
	v_pk_fma_f32 v[186:187], v[202:203], v[202:203], v[186:187]
	v_cvt_pk_bf16_f32 v208, v196, v197
	v_cvt_pk_bf16_f32 v209, v198, v199
	v_cvt_pk_bf16_f32 v210, v200, v201
	v_cvt_pk_bf16_f32 v211, v202, v203
	global_store_dwordx4 v219, v[208:211], s[18:19]
	v_add_f32_dpp v172, v172, v172 row_ror:8 row_mask:0xf bank_mask:0xf
	v_add_f32_dpp v173, v173, v173 row_ror:8 row_mask:0xf bank_mask:0xf
	v_add_f32_dpp v174, v174, v174 row_ror:8 row_mask:0xf bank_mask:0xf
	v_add_f32_dpp v175, v175, v175 row_ror:8 row_mask:0xf bank_mask:0xf
	v_add_f32_dpp v176, v176, v176 row_ror:8 row_mask:0xf bank_mask:0xf
	v_add_f32_dpp v177, v177, v177 row_ror:8 row_mask:0xf bank_mask:0xf
	v_add_f32_dpp v178, v178, v178 row_ror:8 row_mask:0xf bank_mask:0xf
	v_add_f32_dpp v179, v179, v179 row_ror:8 row_mask:0xf bank_mask:0xf
	v_add_f32_dpp v180, v180, v180 row_ror:8 row_mask:0xf bank_mask:0xf
	v_add_f32_dpp v181, v181, v181 row_ror:8 row_mask:0xf bank_mask:0xf
	v_add_f32_dpp v182, v182, v182 row_ror:8 row_mask:0xf bank_mask:0xf
	v_add_f32_dpp v183, v183, v183 row_ror:8 row_mask:0xf bank_mask:0xf
	v_add_f32_dpp v184, v184, v184 row_ror:8 row_mask:0xf bank_mask:0xf
	v_add_f32_dpp v185, v185, v185 row_ror:8 row_mask:0xf bank_mask:0xf
	v_add_f32_dpp v186, v186, v186 row_ror:8 row_mask:0xf bank_mask:0xf
	v_add_f32_dpp v187, v187, v187 row_ror:8 row_mask:0xf bank_mask:0xf
; __device__ __forceinline__ unsigned cvt_pk_bf16(float lo, float hi) { unsigned r; asm volatile("v_cvt_pk_bf16_f32 %0, %1, %2" : "=v"(r) : "v"(lo), "v"(hi)); return r; }
; __device__ __forceinline__ float fgelu(float x) { const float u = x * (1.0f + 0.044715f * x * x); return x * fsigmoid(1.59576912f * u); }
; template <int K> __device__ __forceinline__ float row_ror(float v) { return __int_as_float(__builtin_amdgcn_update_dpp(0, __float_as_int(v), 0x120 + K, 0xF, 0xF, false)); }
;     EPI_ZERO_INIT
;     __device__ __forceinline__ void operator()(AccRef acc, const Unit& u, int sw) const {
;     ...
;             float cs[2][4], cq[2][4];
; #pragma unroll
;             for (int n = 0; n < 2; ++n)
; #pragma unroll
;                 for (int j = 0; j < 4; ++j) { cs[n][j] = 0.f; cq[n][j] = 0.f; }
; #pragma unroll
;             for (int ai = 0; ai < 2; ++ai)
; #pragma unroll
;                 for (int m = 0; m < 4; ++m) { bf16_t* rowp = Vt + ((size_t)(2 * u.pn + bj) * E + (row0 + ai * HALF + m * 16)) * 128 + wc * 32 + 8 * fq;
;                     f32x4 v0 = acc[ai][bj][m][0], v1 = acc[ai][bj][m][1];
; #pragma unroll
;                     for (int j = 0; j < 4; ++j) { v0[j] = fgelu(v0[j]); v1[j] = fgelu(v1[j]);
;                         cs[0][j] += v0[j]; cq[0][j] += v0[j] * v0[j]; cs[1][j] += v1[j]; cq[1][j] += v1[j] * v1[j]; }
;                     u32x4 w; w.x = cvt_pk_bf16(v0[0], v0[1]); w.y = cvt_pk_bf16(v0[2], v0[3]); w.z = cvt_pk_bf16(v1[0], v1[1]); w.w = cvt_pk_bf16(v1[2], v1[3]);
;                     *(u32x4*)rowp = w; }
;     ...
;                 for (int j = 0; j < 4; ++j) { float s = cs[n][j], q = cq[n][j];
;                     s += row_ror<8>(s); q += row_ror<8>(q); s += row_ror<4>(s); q += row_ror<4>(q);
;                     s += row_ror<2>(s); q += row_ror<2>(q); s += row_ror<1>(s); q += row_ror<1>(q);
;                     if (fr == 0) sp[4 * n + j] = (f32x2){s, q}; }
	v_add_f32_dpp v172, v172, v172 row_ror:4 row_mask:0xf bank_mask:0xf
	v_add_f32_dpp v173, v173, v173 row_ror:4 row_mask:0xf bank_mask:0xf
	v_add_f32_dpp v174, v174, v174 row_ror:4 row_mask:0xf bank_mask:0xf
	v_add_f32_dpp v175, v175, v175 row_ror:4 row_mask:0xf bank_mask:0xf
	v_add_f32_dpp v176, v176, v176 row_ror:4 row_mask:0xf bank_mask:0xf
	v_add_f32_dpp v177, v177, v177 row_ror:4 row_mask:0xf bank_mask:0xf
	v_add_f32_dpp v178, v178, v178 row_ror:4 row_mask:0xf bank_mask:0xf
	v_add_f32_dpp v179, v179, v179 row_ror:4 row_mask:0xf bank_mask:0xf
	v_add_f32_dpp v180, v180, v180 row_ror:4 row_mask:0xf bank_mask:0xf
	v_add_f32_dpp v181, v181, v181 row_ror:4 row_mask:0xf bank_mask:0xf
	v_add_f32_dpp v182, v182, v182 row_ror:4 row_mask:0xf bank_mask:0xf
	v_add_f32_dpp v183, v183, v183 row_ror:4 row_mask:0xf bank_mask:0xf
	v_add_f32_dpp v184, v184, v184 row_ror:4 row_mask:0xf bank_mask:0xf
	v_add_f32_dpp v185, v185, v185 row_ror:4 row_mask:0xf bank_mask:0xf
	v_add_f32_dpp v186, v186, v186 row_ror:4 row_mask:0xf bank_mask:0xf
	v_add_f32_dpp v187, v187, v187 row_ror:4 row_mask:0xf bank_mask:0xf
	v_add_f32_dpp v172, v172, v172 row_ror:2 row_mask:0xf bank_mask:0xf
	v_add_f32_dpp v173, v173, v173 row_ror:2 row_mask:0xf bank_mask:0xf
	v_add_f32_dpp v174, v174, v174 row_ror:2 row_mask:0xf bank_mask:0xf
	v_add_f32_dpp v175, v175, v175 row_ror:2 row_mask:0xf bank_mask:0xf
	v_add_f32_dpp v176, v176, v176 row_ror:2 row_mask:0xf bank_mask:0xf
	v_add_f32_dpp v177, v177, v177 row_ror:2 row_mask:0xf bank_mask:0xf
	v_add_f32_dpp v178, v178, v178 row_ror:2 row_mask:0xf bank_mask:0xf
	v_add_f32_dpp v179, v179, v179 row_ror:2 row_mask:0xf bank_mask:0xf
	v_add_f32_dpp v180, v180, v180 row_ror:2 row_mask:0xf bank_mask:0xf
	v_add_f32_dpp v181, v181, v181 row_ror:2 row_mask:0xf bank_mask:0xf
	v_add_f32_dpp v182, v182, v182 row_ror:2 row_mask:0xf bank_mask:0xf
	v_add_f32_dpp v183, v183, v183 row_ror:2 row_mask:0xf bank_mask:0xf
	v_add_f32_dpp v184, v184, v184 row_ror:2 row_mask:0xf bank_mask:0xf
	v_add_f32_dpp v185, v185, v185 row_ror:2 row_mask:0xf bank_mask:0xf
	v_add_f32_dpp v186, v186, v186 row_ror:2 row_mask:0xf bank_mask:0xf
	v_add_f32_dpp v187, v187, v187 row_ror:2 row_mask:0xf bank_mask:0xf
	v_add_f32_dpp v188, v172, v172 row_ror:1 row_mask:0xf bank_mask:0xf
	v_add_f32_dpp v190, v173, v173 row_ror:1 row_mask:0xf bank_mask:0xf
	v_add_f32_dpp v192, v174, v174 row_ror:1 row_mask:0xf bank_mask:0xf
	v_add_f32_dpp v194, v175, v175 row_ror:1 row_mask:0xf bank_mask:0xf
	v_add_f32_dpp v196, v176, v176 row_ror:1 row_mask:0xf bank_mask:0xf
	v_add_f32_dpp v198, v177, v177 row_ror:1 row_mask:0xf bank_mask:0xf
	v_add_f32_dpp v200, v178, v178 row_ror:1 row_mask:0xf bank_mask:0xf
	v_add_f32_dpp v202, v179, v179 row_ror:1 row_mask:0xf bank_mask:0xf
	v_add_f32_dpp v189, v180, v180 row_ror:1 row_mask:0xf bank_mask:0xf
	v_add_f32_dpp v191, v181, v181 row_ror:1 row_mask:0xf bank_mask:0xf
	v_add_f32_dpp v193, v182, v182 row_ror:1 row_mask:0xf bank_mask:0xf
	v_add_f32_dpp v195, v183, v183 row_ror:1 row_mask:0xf bank_mask:0xf
	v_add_f32_dpp v197, v184, v184 row_ror:1 row_mask:0xf bank_mask:0xf
	v_add_f32_dpp v199, v185, v185 row_ror:1 row_mask:0xf bank_mask:0xf
	v_add_f32_dpp v201, v186, v186 row_ror:1 row_mask:0xf bank_mask:0xf
	v_add_f32_dpp v203, v187, v187 row_ror:1 row_mask:0xf bank_mask:0xf
	s_nop 1
	s_mov_b64 exec, vcc
	global_store_dwordx4 v222, v[188:191], s[16:17]
	global_store_dwordx4 v222, v[192:195], s[16:17] offset:16
	global_store_dwordx4 v222, v[196:199], s[16:17] offset:32
	global_store_dwordx4 v222, v[200:203], s[16:17] offset:48
	s_mov_b64 exec, -1
	s_nop 1
	v_mov_b64 v[172:173], 0
	v_mov_b64 v[174:175], 0
	v_mov_b64 v[176:177], 0
	v_mov_b64 v[178:179], 0
	v_mov_b64 v[180:181], 0
	v_mov_b64 v[182:183], 0
	v_mov_b64 v[184:185], 0
	v_mov_b64 v[186:187], 0
	v_pk_mul_f32 v[188:189], v[62:63], v[62:63]
	v_pk_mul_f32 v[190:191], v[64:65], v[64:65]
	v_pk_mul_f32 v[192:193], v[58:59], v[58:59]
	v_pk_mul_f32 v[194:195], v[60:61], v[60:61]
	v_pk_fma_f32 v[188:189], v[188:189], s[0:1], v[224:225] op_sel_hi:[1,0,0]
	v_pk_fma_f32 v[190:191], v[190:191], s[0:1], v[224:225] op_sel_hi:[1,0,0]
	v_pk_fma_f32 v[192:193], v[192:193], s[0:1], v[224:225] op_sel_hi:[1,0,0]
	v_pk_fma_f32 v[194:195], v[194:195], s[0:1], v[224:225] op_sel_hi:[1,0,0]
	v_pk_mul_f32 v[188:189], v[188:189], v[62:63]
	v_pk_mul_f32 v[190:191], v[190:191], v[64:65]
	v_pk_mul_f32 v[192:193], v[192:193], v[58:59]
	v_pk_mul_f32 v[194:195], v[194:195], v[60:61]
	v_exp_f32_e32 v188, v188
	v_exp_f32_e32 v189, v189
	v_exp_f32_e32 v190, v190
	v_exp_f32_e32 v191, v191
	v_exp_f32_e32 v192, v192
	v_exp_f32_e32 v193, v193
	v_exp_f32_e32 v194, v194
	v_exp_f32_e32 v195, v195
	v_pk_add_f32 v[188:189], v[188:189], 1.0 op_sel_hi:[1,0]
	v_pk_add_f32 v[190:191], v[190:191], 1.0 op_sel_hi:[1,0]
	v_pk_add_f32 v[192:193], v[192:193], 1.0 op_sel_hi:[1,0]
	v_pk_add_f32 v[194:195], v[194:195], 1.0 op_sel_hi:[1,0]
	v_rcp_f32_e32 v188, v188
	v_rcp_f32_e32 v189, v189
	v_rcp_f32_e32 v190, v190
	v_rcp_f32_e32 v191, v191
	v_rcp_f32_e32 v192, v192
	v_rcp_f32_e32 v193, v193
	v_rcp_f32_e32 v194, v194
	v_rcp_f32_e32 v195, v195
	v_pk_mul_f32 v[196:197], v[62:63], v[188:189]
	v_pk_mul_f32 v[198:199], v[64:65], v[190:191]
	v_pk_mul_f32 v[200:201], v[58:59], v[192:193]
	v_pk_mul_f32 v[202:203], v[60:61], v[194:195]
	v_pk_add_f32 v[172:173], v[172:173], v[196:197]
	v_pk_add_f32 v[174:175], v[174:175], v[198:199]
	v_pk_add_f32 v[176:177], v[176:177], v[200:201]
	v_pk_add_f32 v[178:179], v[178:179], v[202:203]
	v_pk_fma_f32 v[180:181], v[196:197], v[196:197], v[180:181]
	v_pk_fma_f32 v[182:183], v[198:199], v[198:199], v[182:183]
; __device__ __forceinline__ unsigned cvt_pk_bf16(float lo, float hi) { unsigned r; asm volatile("v_cvt_pk_bf16_f32 %0, %1, %2" : "=v"(r) : "v"(lo), "v"(hi)); return r; }
; __device__ __forceinline__ float fgelu(float x) { const float u = x * (1.0f + 0.044715f * x * x); return x * fsigmoid(1.59576912f * u); }
;     EPI_ZERO_INIT
;     __device__ __forceinline__ void operator()(AccRef acc, const Unit& u, int sw) const {
;     ...
;                 for (int m = 0; m < 4; ++m) { bf16_t* rowp = Vt + ((size_t)(2 * u.pn + bj) * E + (row0 + ai * HALF + m * 16)) * 128 + wc * 32 + 8 * fq;
;                     f32x4 v0 = acc[ai][bj][m][0], v1 = acc[ai][bj][m][1];
; #pragma unroll
;                     for (int j = 0; j < 4; ++j) { v0[j] = fgelu(v0[j]); v1[j] = fgelu(v1[j]);
;                         cs[0][j] += v0[j]; cq[0][j] += v0[j] * v0[j]; cs[1][j] += v1[j]; cq[1][j] += v1[j] * v1[j]; }
;                     u32x4 w; w.x = cvt_pk_bf16(v0[0], v0[1]); w.y = cvt_pk_bf16(v0[2], v0[3]); w.z = cvt_pk_bf16(v1[0], v1[1]); w.w = cvt_pk_bf16(v1[2], v1[3]);
;                     *(u32x4*)rowp = w; }
	v_pk_fma_f32 v[184:185], v[200:201], v[200:201], v[184:185]
	v_pk_fma_f32 v[186:187], v[202:203], v[202:203], v[186:187]
	v_cvt_pk_bf16_f32 v204, v196, v197
	v_cvt_pk_bf16_f32 v205, v198, v199
	v_cvt_pk_bf16_f32 v206, v200, v201
	v_cvt_pk_bf16_f32 v207, v202, v203
	global_store_dwordx4 v212, v[204:207], s[20:21]
	v_pk_mul_f32 v[188:189], v[54:55], v[54:55]
	v_pk_mul_f32 v[190:191], v[56:57], v[56:57]
	v_pk_mul_f32 v[192:193], v[50:51], v[50:51]
	v_pk_mul_f32 v[194:195], v[52:53], v[52:53]
	v_pk_fma_f32 v[188:189], v[188:189], s[0:1], v[224:225] op_sel_hi:[1,0,0]
	v_pk_fma_f32 v[190:191], v[190:191], s[0:1], v[224:225] op_sel_hi:[1,0,0]
	v_pk_fma_f32 v[192:193], v[192:193], s[0:1], v[224:225] op_sel_hi:[1,0,0]
	v_pk_fma_f32 v[194:195], v[194:195], s[0:1], v[224:225] op_sel_hi:[1,0,0]
	v_pk_mul_f32 v[188:189], v[188:189], v[54:55]
	v_pk_mul_f32 v[190:191], v[190:191], v[56:57]
	v_pk_mul_f32 v[192:193], v[192:193], v[50:51]
	v_pk_mul_f32 v[194:195], v[194:195], v[52:53]
	v_exp_f32_e32 v188, v188
	v_exp_f32_e32 v189, v189
	v_exp_f32_e32 v190, v190
	v_exp_f32_e32 v191, v191
	v_exp_f32_e32 v192, v192
	v_exp_f32_e32 v193, v193
	v_exp_f32_e32 v194, v194
	v_exp_f32_e32 v195, v195
	v_pk_add_f32 v[188:189], v[188:189], 1.0 op_sel_hi:[1,0]
	v_pk_add_f32 v[190:191], v[190:191], 1.0 op_sel_hi:[1,0]
	v_pk_add_f32 v[192:193], v[192:193], 1.0 op_sel_hi:[1,0]
	v_pk_add_f32 v[194:195], v[194:195], 1.0 op_sel_hi:[1,0]
	v_rcp_f32_e32 v188, v188
	v_rcp_f32_e32 v189, v189
	v_rcp_f32_e32 v190, v190
	v_rcp_f32_e32 v191, v191
	v_rcp_f32_e32 v192, v192
	v_rcp_f32_e32 v193, v193
	v_rcp_f32_e32 v194, v194
	v_rcp_f32_e32 v195, v195
	v_pk_mul_f32 v[196:197], v[54:55], v[188:189]
	v_pk_mul_f32 v[198:199], v[56:57], v[190:191]
	v_pk_mul_f32 v[200:201], v[50:51], v[192:193]
	v_pk_mul_f32 v[202:203], v[52:53], v[194:195]
	v_pk_add_f32 v[172:173], v[172:173], v[196:197]
	v_pk_add_f32 v[174:175], v[174:175], v[198:199]
	v_pk_add_f32 v[176:177], v[176:177], v[200:201]
	v_pk_add_f32 v[178:179], v[178:179], v[202:203]
	v_pk_fma_f32 v[180:181], v[196:197], v[196:197], v[180:181]
	v_pk_fma_f32 v[182:183], v[198:199], v[198:199], v[182:183]
	v_pk_fma_f32 v[184:185], v[200:201], v[200:201], v[184:185]
	v_pk_fma_f32 v[186:187], v[202:203], v[202:203], v[186:187]
	v_cvt_pk_bf16_f32 v208, v196, v197
	v_cvt_pk_bf16_f32 v209, v198, v199
	v_cvt_pk_bf16_f32 v210, v200, v201
	v_cvt_pk_bf16_f32 v211, v202, v203
	global_store_dwordx4 v213, v[208:211], s[20:21]
	v_pk_mul_f32 v[188:189], v[26:27], v[26:27]
	v_pk_mul_f32 v[190:191], v[28:29], v[28:29]
	v_pk_mul_f32 v[192:193], v[46:47], v[46:47]
	v_pk_mul_f32 v[194:195], v[48:49], v[48:49]
	v_pk_fma_f32 v[188:189], v[188:189], s[0:1], v[224:225] op_sel_hi:[1,0,0]
	v_pk_fma_f32 v[190:191], v[190:191], s[0:1], v[224:225] op_sel_hi:[1,0,0]
	v_pk_fma_f32 v[192:193], v[192:193], s[0:1], v[224:225] op_sel_hi:[1,0,0]
	v_pk_fma_f32 v[194:195], v[194:195], s[0:1], v[224:225] op_sel_hi:[1,0,0]
	v_pk_mul_f32 v[188:189], v[188:189], v[26:27]
	v_pk_mul_f32 v[190:191], v[190:191], v[28:29]
	v_pk_mul_f32 v[192:193], v[192:193], v[46:47]
	v_pk_mul_f32 v[194:195], v[194:195], v[48:49]
	v_exp_f32_e32 v188, v188
	v_exp_f32_e32 v189, v189
	v_exp_f32_e32 v190, v190
	v_exp_f32_e32 v191, v191
	v_exp_f32_e32 v192, v192
	v_exp_f32_e32 v193, v193
	v_exp_f32_e32 v194, v194
	v_exp_f32_e32 v195, v195
	v_pk_add_f32 v[188:189], v[188:189], 1.0 op_sel_hi:[1,0]
	v_pk_add_f32 v[190:191], v[190:191], 1.0 op_sel_hi:[1,0]
	v_pk_add_f32 v[192:193], v[192:193], 1.0 op_sel_hi:[1,0]
	v_pk_add_f32 v[194:195], v[194:195], 1.0 op_sel_hi:[1,0]
	v_rcp_f32_e32 v188, v188
	v_rcp_f32_e32 v189, v189
	v_rcp_f32_e32 v190, v190
	v_rcp_f32_e32 v191, v191
	v_rcp_f32_e32 v192, v192
	v_rcp_f32_e32 v193, v193
	v_rcp_f32_e32 v194, v194
	v_rcp_f32_e32 v195, v195
	v_pk_mul_f32 v[196:197], v[26:27], v[188:189]
	v_pk_mul_f32 v[198:199], v[28:29], v[190:191]
	v_pk_mul_f32 v[200:201], v[46:47], v[192:193]
	v_pk_mul_f32 v[202:203], v[48:49], v[194:195]
	v_pk_add_f32 v[172:173], v[172:173], v[196:197]
	v_pk_add_f32 v[174:175], v[174:175], v[198:199]
	v_pk_add_f32 v[176:177], v[176:177], v[200:201]
	v_pk_add_f32 v[178:179], v[178:179], v[202:203]
	v_pk_fma_f32 v[180:181], v[196:197], v[196:197], v[180:181]
	v_pk_fma_f32 v[182:183], v[198:199], v[198:199], v[182:183]
	v_pk_fma_f32 v[184:185], v[200:201], v[200:201], v[184:185]
	v_pk_fma_f32 v[186:187], v[202:203], v[202:203], v[186:187]
	v_cvt_pk_bf16_f32 v204, v196, v197
	v_cvt_pk_bf16_f32 v205, v198, v199
	v_cvt_pk_bf16_f32 v206, v200, v201
	v_cvt_pk_bf16_f32 v207, v202, v203
	global_store_dwordx4 v214, v[204:207], s[20:21]
	v_pk_mul_f32 v[188:189], v[22:23], v[22:23]
	v_pk_mul_f32 v[190:191], v[24:25], v[24:25]
	v_pk_mul_f32 v[192:193], v[42:43], v[42:43]
	v_pk_mul_f32 v[194:195], v[44:45], v[44:45]
	v_pk_fma_f32 v[188:189], v[188:189], s[0:1], v[224:225] op_sel_hi:[1,0,0]
	v_pk_fma_f32 v[190:191], v[190:191], s[0:1], v[224:225] op_sel_hi:[1,0,0]
	v_pk_fma_f32 v[192:193], v[192:193], s[0:1], v[224:225] op_sel_hi:[1,0,0]
	v_pk_fma_f32 v[194:195], v[194:195], s[0:1], v[224:225] op_sel_hi:[1,0,0]
	v_pk_mul_f32 v[188:189], v[188:189], v[22:23]
	v_pk_mul_f32 v[190:191], v[190:191], v[24:25]
	v_pk_mul_f32 v[192:193], v[192:193], v[42:43]
	v_pk_mul_f32 v[194:195], v[194:195], v[44:45]
	v_exp_f32_e32 v188, v188
	v_exp_f32_e32 v189, v189
	v_exp_f32_e32 v190, v190
	v_exp_f32_e32 v191, v191
	v_exp_f32_e32 v192, v192
	v_exp_f32_e32 v193, v193
	v_exp_f32_e32 v194, v194
	v_exp_f32_e32 v195, v195
	v_pk_add_f32 v[188:189], v[188:189], 1.0 op_sel_hi:[1,0]
	v_pk_add_f32 v[190:191], v[190:191], 1.0 op_sel_hi:[1,0]
	v_pk_add_f32 v[192:193], v[192:193], 1.0 op_sel_hi:[1,0]
; __device__ __forceinline__ unsigned cvt_pk_bf16(float lo, float hi) { unsigned r; asm volatile("v_cvt_pk_bf16_f32 %0, %1, %2" : "=v"(r) : "v"(lo), "v"(hi)); return r; }
; __device__ __forceinline__ float fgelu(float x) { const float u = x * (1.0f + 0.044715f * x * x); return x * fsigmoid(1.59576912f * u); }
;     EPI_ZERO_INIT
;     __device__ __forceinline__ void operator()(AccRef acc, const Unit& u, int sw) const {
;     ...
;                 for (int m = 0; m < 4; ++m) { bf16_t* rowp = Vt + ((size_t)(2 * u.pn + bj) * E + (row0 + ai * HALF + m * 16)) * 128 + wc * 32 + 8 * fq;
;                     f32x4 v0 = acc[ai][bj][m][0], v1 = acc[ai][bj][m][1];
; #pragma unroll
;                     for (int j = 0; j < 4; ++j) { v0[j] = fgelu(v0[j]); v1[j] = fgelu(v1[j]);
;                         cs[0][j] += v0[j]; cq[0][j] += v0[j] * v0[j]; cs[1][j] += v1[j]; cq[1][j] += v1[j] * v1[j]; }
;                     u32x4 w; w.x = cvt_pk_bf16(v0[0], v0[1]); w.y = cvt_pk_bf16(v0[2], v0[3]); w.z = cvt_pk_bf16(v1[0], v1[1]); w.w = cvt_pk_bf16(v1[2], v1[3]);
;                     *(u32x4*)rowp = w; }
	v_pk_add_f32 v[194:195], v[194:195], 1.0 op_sel_hi:[1,0]
	v_rcp_f32_e32 v188, v188
	v_rcp_f32_e32 v189, v189
	v_rcp_f32_e32 v190, v190
	v_rcp_f32_e32 v191, v191
	v_rcp_f32_e32 v192, v192
	v_rcp_f32_e32 v193, v193
	v_rcp_f32_e32 v194, v194
	v_rcp_f32_e32 v195, v195
	v_pk_mul_f32 v[196:197], v[22:23], v[188:189]
	v_pk_mul_f32 v[198:199], v[24:25], v[190:191]
	v_pk_mul_f32 v[200:201], v[42:43], v[192:193]
	v_pk_mul_f32 v[202:203], v[44:45], v[194:195]
	v_pk_add_f32 v[172:173], v[172:173], v[196:197]
	v_pk_add_f32 v[174:175], v[174:175], v[198:199]
	v_pk_add_f32 v[176:177], v[176:177], v[200:201]
	v_pk_add_f32 v[178:179], v[178:179], v[202:203]
	v_pk_fma_f32 v[180:181], v[196:197], v[196:197], v[180:181]
	v_pk_fma_f32 v[182:183], v[198:199], v[198:199], v[182:183]
	v_pk_fma_f32 v[184:185], v[200:201], v[200:201], v[184:185]
	v_pk_fma_f32 v[186:187], v[202:203], v[202:203], v[186:187]
	v_cvt_pk_bf16_f32 v208, v196, v197
	v_cvt_pk_bf16_f32 v209, v198, v199
	v_cvt_pk_bf16_f32 v210, v200, v201
	v_cvt_pk_bf16_f32 v211, v202, v203
	global_store_dwordx4 v215, v[208:211], s[20:21]
	v_pk_mul_f32 v[188:189], v[14:15], v[14:15]
	v_pk_mul_f32 v[190:191], v[16:17], v[16:17]
	v_pk_mul_f32 v[192:193], v[38:39], v[38:39]
	v_pk_mul_f32 v[194:195], v[40:41], v[40:41]
	v_pk_fma_f32 v[188:189], v[188:189], s[0:1], v[224:225] op_sel_hi:[1,0,0]
	v_pk_fma_f32 v[190:191], v[190:191], s[0:1], v[224:225] op_sel_hi:[1,0,0]
	v_pk_fma_f32 v[192:193], v[192:193], s[0:1], v[224:225] op_sel_hi:[1,0,0]
	v_pk_fma_f32 v[194:195], v[194:195], s[0:1], v[224:225] op_sel_hi:[1,0,0]
	v_pk_mul_f32 v[188:189], v[188:189], v[14:15]
	v_pk_mul_f32 v[190:191], v[190:191], v[16:17]
	v_pk_mul_f32 v[192:193], v[192:193], v[38:39]
	v_pk_mul_f32 v[194:195], v[194:195], v[40:41]
	v_exp_f32_e32 v188, v188
	v_exp_f32_e32 v189, v189
	v_exp_f32_e32 v190, v190
	v_exp_f32_e32 v191, v191
	v_exp_f32_e32 v192, v192
	v_exp_f32_e32 v193, v193
	v_exp_f32_e32 v194, v194
	v_exp_f32_e32 v195, v195
	v_pk_add_f32 v[188:189], v[188:189], 1.0 op_sel_hi:[1,0]
	v_pk_add_f32 v[190:191], v[190:191], 1.0 op_sel_hi:[1,0]
	v_pk_add_f32 v[192:193], v[192:193], 1.0 op_sel_hi:[1,0]
	v_pk_add_f32 v[194:195], v[194:195], 1.0 op_sel_hi:[1,0]
	v_rcp_f32_e32 v188, v188
	v_rcp_f32_e32 v189, v189
	v_rcp_f32_e32 v190, v190
	v_rcp_f32_e32 v191, v191
	v_rcp_f32_e32 v192, v192
	v_rcp_f32_e32 v193, v193
	v_rcp_f32_e32 v194, v194
	v_rcp_f32_e32 v195, v195
	v_pk_mul_f32 v[196:197], v[14:15], v[188:189]
	v_pk_mul_f32 v[198:199], v[16:17], v[190:191]
	v_pk_mul_f32 v[200:201], v[38:39], v[192:193]
	v_pk_mul_f32 v[202:203], v[40:41], v[194:195]
	v_pk_add_f32 v[172:173], v[172:173], v[196:197]
	v_pk_add_f32 v[174:175], v[174:175], v[198:199]
	v_pk_add_f32 v[176:177], v[176:177], v[200:201]
	v_pk_add_f32 v[178:179], v[178:179], v[202:203]
	v_pk_fma_f32 v[180:181], v[196:197], v[196:197], v[180:181]
	v_pk_fma_f32 v[182:183], v[198:199], v[198:199], v[182:183]
	v_pk_fma_f32 v[184:185], v[200:201], v[200:201], v[184:185]
	v_pk_fma_f32 v[186:187], v[202:203], v[202:203], v[186:187]
	v_cvt_pk_bf16_f32 v204, v196, v197
	v_cvt_pk_bf16_f32 v205, v198, v199
	v_cvt_pk_bf16_f32 v206, v200, v201
	v_cvt_pk_bf16_f32 v207, v202, v203
	global_store_dwordx4 v216, v[204:207], s[20:21]
	v_pk_mul_f32 v[188:189], v[10:11], v[10:11]
	v_pk_mul_f32 v[190:191], v[12:13], v[12:13]
	v_pk_mul_f32 v[192:193], v[34:35], v[34:35]
	v_pk_mul_f32 v[194:195], v[36:37], v[36:37]
	v_pk_fma_f32 v[188:189], v[188:189], s[0:1], v[224:225] op_sel_hi:[1,0,0]
	v_pk_fma_f32 v[190:191], v[190:191], s[0:1], v[224:225] op_sel_hi:[1,0,0]
	v_pk_fma_f32 v[192:193], v[192:193], s[0:1], v[224:225] op_sel_hi:[1,0,0]
	v_pk_fma_f32 v[194:195], v[194:195], s[0:1], v[224:225] op_sel_hi:[1,0,0]
	v_pk_mul_f32 v[188:189], v[188:189], v[10:11]
	v_pk_mul_f32 v[190:191], v[190:191], v[12:13]
	v_pk_mul_f32 v[192:193], v[192:193], v[34:35]
	v_pk_mul_f32 v[194:195], v[194:195], v[36:37]
	v_exp_f32_e32 v188, v188
	v_exp_f32_e32 v189, v189
	v_exp_f32_e32 v190, v190
	v_exp_f32_e32 v191, v191
	v_exp_f32_e32 v192, v192
	v_exp_f32_e32 v193, v193
	v_exp_f32_e32 v194, v194
	v_exp_f32_e32 v195, v195
	v_pk_add_f32 v[188:189], v[188:189], 1.0 op_sel_hi:[1,0]
	v_pk_add_f32 v[190:191], v[190:191], 1.0 op_sel_hi:[1,0]
	v_pk_add_f32 v[192:193], v[192:193], 1.0 op_sel_hi:[1,0]
	v_pk_add_f32 v[194:195], v[194:195], 1.0 op_sel_hi:[1,0]
	v_rcp_f32_e32 v188, v188
	v_rcp_f32_e32 v189, v189
	v_rcp_f32_e32 v190, v190
	v_rcp_f32_e32 v191, v191
	v_rcp_f32_e32 v192, v192
	v_rcp_f32_e32 v193, v193
	v_rcp_f32_e32 v194, v194
	v_rcp_f32_e32 v195, v195
	v_pk_mul_f32 v[196:197], v[10:11], v[188:189]
	v_pk_mul_f32 v[198:199], v[12:13], v[190:191]
	v_pk_mul_f32 v[200:201], v[34:35], v[192:193]
	v_pk_mul_f32 v[202:203], v[36:37], v[194:195]
	v_pk_add_f32 v[172:173], v[172:173], v[196:197]
	v_pk_add_f32 v[174:175], v[174:175], v[198:199]
	v_pk_add_f32 v[176:177], v[176:177], v[200:201]
	v_pk_add_f32 v[178:179], v[178:179], v[202:203]
	v_pk_fma_f32 v[180:181], v[196:197], v[196:197], v[180:181]
	v_pk_fma_f32 v[182:183], v[198:199], v[198:199], v[182:183]
	v_pk_fma_f32 v[184:185], v[200:201], v[200:201], v[184:185]
	v_pk_fma_f32 v[186:187], v[202:203], v[202:203], v[186:187]
	v_cvt_pk_bf16_f32 v208, v196, v197
	v_cvt_pk_bf16_f32 v209, v198, v199
	v_cvt_pk_bf16_f32 v210, v200, v201
	v_cvt_pk_bf16_f32 v211, v202, v203
	global_store_dwordx4 v217, v[208:211], s[20:21]
	v_pk_mul_f32 v[188:189], v[6:7], v[6:7]
	v_pk_mul_f32 v[190:191], v[8:9], v[8:9]
	v_pk_mul_f32 v[192:193], v[30:31], v[30:31]
	v_pk_mul_f32 v[194:195], v[32:33], v[32:33]
	v_pk_fma_f32 v[188:189], v[188:189], s[0:1], v[224:225] op_sel_hi:[1,0,0]
; __device__ __forceinline__ unsigned cvt_pk_bf16(float lo, float hi) { unsigned r; asm volatile("v_cvt_pk_bf16_f32 %0, %1, %2" : "=v"(r) : "v"(lo), "v"(hi)); return r; }
; __device__ __forceinline__ float fgelu(float x) { const float u = x * (1.0f + 0.044715f * x * x); return x * fsigmoid(1.59576912f * u); }
; template <int K> __device__ __forceinline__ float row_ror(float v) { return __int_as_float(__builtin_amdgcn_update_dpp(0, __float_as_int(v), 0x120 + K, 0xF, 0xF, false)); }
;     EPI_ZERO_INIT
;     __device__ __forceinline__ void operator()(AccRef acc, const Unit& u, int sw) const {
;     ...
;                 for (int m = 0; m < 4; ++m) { bf16_t* rowp = Vt + ((size_t)(2 * u.pn + bj) * E + (row0 + ai * HALF + m * 16)) * 128 + wc * 32 + 8 * fq;
;                     f32x4 v0 = acc[ai][bj][m][0], v1 = acc[ai][bj][m][1];
; #pragma unroll
;                     for (int j = 0; j < 4; ++j) { v0[j] = fgelu(v0[j]); v1[j] = fgelu(v1[j]);
;                         cs[0][j] += v0[j]; cq[0][j] += v0[j] * v0[j]; cs[1][j] += v1[j]; cq[1][j] += v1[j] * v1[j]; }
;                     u32x4 w; w.x = cvt_pk_bf16(v0[0], v0[1]); w.y = cvt_pk_bf16(v0[2], v0[3]); w.z = cvt_pk_bf16(v1[0], v1[1]); w.w = cvt_pk_bf16(v1[2], v1[3]);
;                     *(u32x4*)rowp = w; }
;             f32x2* sp = VSTAT + (size_t)(u.pm * 2 + wr) * M + col0 + bj * HALF;
; #pragma unroll
;             for (int n = 0; n < 2; ++n)
; #pragma unroll
;                 for (int j = 0; j < 4; ++j) { float s = cs[n][j], q = cq[n][j];
;                     s += row_ror<8>(s); q += row_ror<8>(q); s += row_ror<4>(s); q += row_ror<4>(q);
;                     s += row_ror<2>(s); q += row_ror<2>(q); s += row_ror<1>(s); q += row_ror<1>(q);
	v_pk_fma_f32 v[190:191], v[190:191], s[0:1], v[224:225] op_sel_hi:[1,0,0]
	v_pk_fma_f32 v[192:193], v[192:193], s[0:1], v[224:225] op_sel_hi:[1,0,0]
	v_pk_fma_f32 v[194:195], v[194:195], s[0:1], v[224:225] op_sel_hi:[1,0,0]
	v_pk_mul_f32 v[188:189], v[188:189], v[6:7]
	v_pk_mul_f32 v[190:191], v[190:191], v[8:9]
	v_pk_mul_f32 v[192:193], v[192:193], v[30:31]
	v_pk_mul_f32 v[194:195], v[194:195], v[32:33]
	v_exp_f32_e32 v188, v188
	v_exp_f32_e32 v189, v189
	v_exp_f32_e32 v190, v190
	v_exp_f32_e32 v191, v191
	v_exp_f32_e32 v192, v192
	v_exp_f32_e32 v193, v193
	v_exp_f32_e32 v194, v194
	v_exp_f32_e32 v195, v195
	v_pk_add_f32 v[188:189], v[188:189], 1.0 op_sel_hi:[1,0]
	v_pk_add_f32 v[190:191], v[190:191], 1.0 op_sel_hi:[1,0]
	v_pk_add_f32 v[192:193], v[192:193], 1.0 op_sel_hi:[1,0]
	v_pk_add_f32 v[194:195], v[194:195], 1.0 op_sel_hi:[1,0]
	v_rcp_f32_e32 v188, v188
	v_rcp_f32_e32 v189, v189
	v_rcp_f32_e32 v190, v190
	v_rcp_f32_e32 v191, v191
	v_rcp_f32_e32 v192, v192
	v_rcp_f32_e32 v193, v193
	v_rcp_f32_e32 v194, v194
	v_rcp_f32_e32 v195, v195
	v_pk_mul_f32 v[196:197], v[6:7], v[188:189]
	v_pk_mul_f32 v[198:199], v[8:9], v[190:191]
	v_pk_mul_f32 v[200:201], v[30:31], v[192:193]
	v_pk_mul_f32 v[202:203], v[32:33], v[194:195]
	v_pk_add_f32 v[172:173], v[172:173], v[196:197]
	v_pk_add_f32 v[174:175], v[174:175], v[198:199]
	v_pk_add_f32 v[176:177], v[176:177], v[200:201]
	v_pk_add_f32 v[178:179], v[178:179], v[202:203]
	v_pk_fma_f32 v[180:181], v[196:197], v[196:197], v[180:181]
	v_pk_fma_f32 v[182:183], v[198:199], v[198:199], v[182:183]
	v_pk_fma_f32 v[184:185], v[200:201], v[200:201], v[184:185]
	v_pk_fma_f32 v[186:187], v[202:203], v[202:203], v[186:187]
	v_cvt_pk_bf16_f32 v204, v196, v197
	v_cvt_pk_bf16_f32 v205, v198, v199
	v_cvt_pk_bf16_f32 v206, v200, v201
	v_cvt_pk_bf16_f32 v207, v202, v203
	global_store_dwordx4 v218, v[204:207], s[20:21]
	v_pk_mul_f32 v[188:189], v[2:3], v[2:3]
	v_pk_mul_f32 v[190:191], v[4:5], v[4:5]
	v_pk_mul_f32 v[192:193], v[18:19], v[18:19]
	v_pk_mul_f32 v[194:195], v[20:21], v[20:21]
	v_pk_fma_f32 v[188:189], v[188:189], s[0:1], v[224:225] op_sel_hi:[1,0,0]
	v_pk_fma_f32 v[190:191], v[190:191], s[0:1], v[224:225] op_sel_hi:[1,0,0]
	v_pk_fma_f32 v[192:193], v[192:193], s[0:1], v[224:225] op_sel_hi:[1,0,0]
	v_pk_fma_f32 v[194:195], v[194:195], s[0:1], v[224:225] op_sel_hi:[1,0,0]
	v_pk_mul_f32 v[188:189], v[188:189], v[2:3]
	v_pk_mul_f32 v[190:191], v[190:191], v[4:5]
	v_pk_mul_f32 v[192:193], v[192:193], v[18:19]
	v_pk_mul_f32 v[194:195], v[194:195], v[20:21]
	v_exp_f32_e32 v188, v188
	v_exp_f32_e32 v189, v189
	v_exp_f32_e32 v190, v190
	v_exp_f32_e32 v191, v191
	v_exp_f32_e32 v192, v192
	v_exp_f32_e32 v193, v193
	v_exp_f32_e32 v194, v194
	v_exp_f32_e32 v195, v195
	v_pk_add_f32 v[188:189], v[188:189], 1.0 op_sel_hi:[1,0]
	v_pk_add_f32 v[190:191], v[190:191], 1.0 op_sel_hi:[1,0]
	v_pk_add_f32 v[192:193], v[192:193], 1.0 op_sel_hi:[1,0]
	v_pk_add_f32 v[194:195], v[194:195], 1.0 op_sel_hi:[1,0]
	v_rcp_f32_e32 v188, v188
	v_rcp_f32_e32 v189, v189
	v_rcp_f32_e32 v190, v190
	v_rcp_f32_e32 v191, v191
	v_rcp_f32_e32 v192, v192
	v_rcp_f32_e32 v193, v193
	v_rcp_f32_e32 v194, v194
	v_rcp_f32_e32 v195, v195
	v_pk_mul_f32 v[196:197], v[2:3], v[188:189]
	v_pk_mul_f32 v[198:199], v[4:5], v[190:191]
	v_pk_mul_f32 v[200:201], v[18:19], v[192:193]
	v_pk_mul_f32 v[202:203], v[20:21], v[194:195]
	v_pk_add_f32 v[172:173], v[172:173], v[196:197]
	v_pk_add_f32 v[174:175], v[174:175], v[198:199]
	v_pk_add_f32 v[176:177], v[176:177], v[200:201]
	v_pk_add_f32 v[178:179], v[178:179], v[202:203]
	v_pk_fma_f32 v[180:181], v[196:197], v[196:197], v[180:181]
	v_pk_fma_f32 v[182:183], v[198:199], v[198:199], v[182:183]
	v_pk_fma_f32 v[184:185], v[200:201], v[200:201], v[184:185]
	v_pk_fma_f32 v[186:187], v[202:203], v[202:203], v[186:187]
	v_cvt_pk_bf16_f32 v208, v196, v197
	v_cvt_pk_bf16_f32 v209, v198, v199
	v_cvt_pk_bf16_f32 v210, v200, v201
	v_cvt_pk_bf16_f32 v211, v202, v203
	global_store_dwordx4 v219, v[208:211], s[20:21]
	v_add_f32_dpp v172, v172, v172 row_ror:8 row_mask:0xf bank_mask:0xf
	v_add_f32_dpp v173, v173, v173 row_ror:8 row_mask:0xf bank_mask:0xf
	v_add_f32_dpp v174, v174, v174 row_ror:8 row_mask:0xf bank_mask:0xf
	v_add_f32_dpp v175, v175, v175 row_ror:8 row_mask:0xf bank_mask:0xf
	v_add_f32_dpp v176, v176, v176 row_ror:8 row_mask:0xf bank_mask:0xf
; template <int K> __device__ __forceinline__ float row_ror(float v) { return __int_as_float(__builtin_amdgcn_update_dpp(0, __float_as_int(v), 0x120 + K, 0xF, 0xF, false)); }
;     EPI_ZERO_INIT
;     __device__ __forceinline__ void operator()(AccRef acc, const Unit& u, int sw) const {
;     ...
;                 for (int j = 0; j < 4; ++j) { float s = cs[n][j], q = cq[n][j];
;                     s += row_ror<8>(s); q += row_ror<8>(q); s += row_ror<4>(s); q += row_ror<4>(q);
;                     s += row_ror<2>(s); q += row_ror<2>(q); s += row_ror<1>(s); q += row_ror<1>(q);
;                     if (fr == 0) sp[4 * n + j] = (f32x2){s, q}; }
	v_add_f32_dpp v177, v177, v177 row_ror:8 row_mask:0xf bank_mask:0xf
	v_add_f32_dpp v178, v178, v178 row_ror:8 row_mask:0xf bank_mask:0xf
	v_add_f32_dpp v179, v179, v179 row_ror:8 row_mask:0xf bank_mask:0xf
	v_add_f32_dpp v180, v180, v180 row_ror:8 row_mask:0xf bank_mask:0xf
	v_add_f32_dpp v181, v181, v181 row_ror:8 row_mask:0xf bank_mask:0xf
	v_add_f32_dpp v182, v182, v182 row_ror:8 row_mask:0xf bank_mask:0xf
	v_add_f32_dpp v183, v183, v183 row_ror:8 row_mask:0xf bank_mask:0xf
	v_add_f32_dpp v184, v184, v184 row_ror:8 row_mask:0xf bank_mask:0xf
	v_add_f32_dpp v185, v185, v185 row_ror:8 row_mask:0xf bank_mask:0xf
	v_add_f32_dpp v186, v186, v186 row_ror:8 row_mask:0xf bank_mask:0xf
	v_add_f32_dpp v187, v187, v187 row_ror:8 row_mask:0xf bank_mask:0xf
	v_add_f32_dpp v172, v172, v172 row_ror:4 row_mask:0xf bank_mask:0xf
	v_add_f32_dpp v173, v173, v173 row_ror:4 row_mask:0xf bank_mask:0xf
	v_add_f32_dpp v174, v174, v174 row_ror:4 row_mask:0xf bank_mask:0xf
	v_add_f32_dpp v175, v175, v175 row_ror:4 row_mask:0xf bank_mask:0xf
	v_add_f32_dpp v176, v176, v176 row_ror:4 row_mask:0xf bank_mask:0xf
	v_add_f32_dpp v177, v177, v177 row_ror:4 row_mask:0xf bank_mask:0xf
	v_add_f32_dpp v178, v178, v178 row_ror:4 row_mask:0xf bank_mask:0xf
	v_add_f32_dpp v179, v179, v179 row_ror:4 row_mask:0xf bank_mask:0xf
	v_add_f32_dpp v180, v180, v180 row_ror:4 row_mask:0xf bank_mask:0xf
	v_add_f32_dpp v181, v181, v181 row_ror:4 row_mask:0xf bank_mask:0xf
	v_add_f32_dpp v182, v182, v182 row_ror:4 row_mask:0xf bank_mask:0xf
	v_add_f32_dpp v183, v183, v183 row_ror:4 row_mask:0xf bank_mask:0xf
	v_add_f32_dpp v184, v184, v184 row_ror:4 row_mask:0xf bank_mask:0xf
	v_add_f32_dpp v185, v185, v185 row_ror:4 row_mask:0xf bank_mask:0xf
	v_add_f32_dpp v186, v186, v186 row_ror:4 row_mask:0xf bank_mask:0xf
	v_add_f32_dpp v187, v187, v187 row_ror:4 row_mask:0xf bank_mask:0xf
	v_add_f32_dpp v172, v172, v172 row_ror:2 row_mask:0xf bank_mask:0xf
	v_add_f32_dpp v173, v173, v173 row_ror:2 row_mask:0xf bank_mask:0xf
	v_add_f32_dpp v174, v174, v174 row_ror:2 row_mask:0xf bank_mask:0xf
	v_add_f32_dpp v175, v175, v175 row_ror:2 row_mask:0xf bank_mask:0xf
	v_add_f32_dpp v176, v176, v176 row_ror:2 row_mask:0xf bank_mask:0xf
	v_add_f32_dpp v177, v177, v177 row_ror:2 row_mask:0xf bank_mask:0xf
	v_add_f32_dpp v178, v178, v178 row_ror:2 row_mask:0xf bank_mask:0xf
	v_add_f32_dpp v179, v179, v179 row_ror:2 row_mask:0xf bank_mask:0xf
	v_add_f32_dpp v180, v180, v180 row_ror:2 row_mask:0xf bank_mask:0xf
	v_add_f32_dpp v181, v181, v181 row_ror:2 row_mask:0xf bank_mask:0xf
	v_add_f32_dpp v182, v182, v182 row_ror:2 row_mask:0xf bank_mask:0xf
	v_add_f32_dpp v183, v183, v183 row_ror:2 row_mask:0xf bank_mask:0xf
	v_add_f32_dpp v184, v184, v184 row_ror:2 row_mask:0xf bank_mask:0xf
	v_add_f32_dpp v185, v185, v185 row_ror:2 row_mask:0xf bank_mask:0xf
	v_add_f32_dpp v186, v186, v186 row_ror:2 row_mask:0xf bank_mask:0xf
	v_add_f32_dpp v187, v187, v187 row_ror:2 row_mask:0xf bank_mask:0xf
	v_add_f32_dpp v188, v172, v172 row_ror:1 row_mask:0xf bank_mask:0xf
	v_add_f32_dpp v190, v173, v173 row_ror:1 row_mask:0xf bank_mask:0xf
	v_add_f32_dpp v192, v174, v174 row_ror:1 row_mask:0xf bank_mask:0xf
	v_add_f32_dpp v194, v175, v175 row_ror:1 row_mask:0xf bank_mask:0xf
	v_add_f32_dpp v196, v176, v176 row_ror:1 row_mask:0xf bank_mask:0xf
	v_add_f32_dpp v198, v177, v177 row_ror:1 row_mask:0xf bank_mask:0xf
	v_add_f32_dpp v200, v178, v178 row_ror:1 row_mask:0xf bank_mask:0xf
	v_add_f32_dpp v202, v179, v179 row_ror:1 row_mask:0xf bank_mask:0xf
	v_add_f32_dpp v189, v180, v180 row_ror:1 row_mask:0xf bank_mask:0xf
	v_add_f32_dpp v191, v181, v181 row_ror:1 row_mask:0xf bank_mask:0xf
	v_add_f32_dpp v193, v182, v182 row_ror:1 row_mask:0xf bank_mask:0xf
	v_add_f32_dpp v195, v183, v183 row_ror:1 row_mask:0xf bank_mask:0xf
	v_add_f32_dpp v197, v184, v184 row_ror:1 row_mask:0xf bank_mask:0xf
	v_add_f32_dpp v199, v185, v185 row_ror:1 row_mask:0xf bank_mask:0xf
	v_add_f32_dpp v201, v186, v186 row_ror:1 row_mask:0xf bank_mask:0xf
	v_add_f32_dpp v203, v187, v187 row_ror:1 row_mask:0xf bank_mask:0xf
	s_nop 1
	s_mov_b64 exec, vcc
	global_store_dwordx4 v222, v[188:191], s[16:17] offset:1024
	global_store_dwordx4 v222, v[192:195], s[16:17] offset:1040
	global_store_dwordx4 v222, v[196:199], s[16:17] offset:1056
	global_store_dwordx4 v222, v[200:203], s[16:17] offset:1072
	s_mov_b64 exec, -1
	s_nop 1
	s_branch .LBB0_767
